# same edits as before with the remaining software wait states re-checked: scan LDS reads earlier, two y stores per chunk, GEMM epilogue row loads batched ahead of the stores
# baseline (speedup 1.0000x reference)
.LBB0_1069:
	s_bitcmp1_b32 s52, 0
	s_cselect_b32 s10, 0x6000, 0
	s_add_i32 s10, s97, s10
	v_lshl_add_u32 v83, v75, 2, s10
	ds_read_b128 v[126:129], v83
	ds_read_b128 v[130:133], v83 offset:16
	ds_read_b128 v[134:137], v83 offset:512
	ds_read_b128 v[62:65], v83 offset:528
	ds_read_b128 v[58:61], v83 offset:256
	ds_read_b128 v[54:57], v83 offset:272
	s_lshl_b32 s11, s4, 2
	s_add_i32 s10, s10, s11
	v_lshl_add_u32 v82, v72, 2, s10
	s_waitcnt lgkmcnt(5)
	v_mul_f32_e32 v67, v46, v126
	v_mul_f32_e32 v68, v38, v126
	v_fmac_f32_e32 v67, v47, v127
	v_fmac_f32_e32 v68, v39, v127
	v_fmac_f32_e32 v67, v48, v128
	v_fmac_f32_e32 v68, v40, v128
	v_fmac_f32_e32 v67, v49, v129
	v_fmac_f32_e32 v68, v41, v129
	s_waitcnt lgkmcnt(4)
	v_fmac_f32_e32 v67, v42, v130
	v_fmac_f32_e32 v68, v34, v130
	v_fmac_f32_e32 v67, v43, v131
	v_fmac_f32_e32 v68, v35, v131
	v_fmac_f32_e32 v67, v44, v132
	v_fmac_f32_e32 v68, v36, v132
	v_fmac_f32_e32 v67, v45, v133
	v_fmac_f32_e32 v68, v37, v133
	v_add_u32_e32 v66, 0x100, v82
	ds_read2st64_b64 v[50:53], v66 offset0:2 offset1:5
	ds_read_b128 v[138:141], v83 offset:768
	ds_read_b128 v[142:145], v83 offset:784
	ds_read_b128 v[126:129], v83 offset:1536
	ds_read_b128 v[130:133], v83 offset:1552
	s_nop 1
	v_add_f32_dpp v67, v67, v67 quad_perm:[1,0,3,2] row_mask:0xf bank_mask:0xf bound_ctrl:1
	v_add_f32_dpp v68, v68, v68 quad_perm:[1,0,3,2] row_mask:0xf bank_mask:0xf bound_ctrl:1
	s_nop 0
	v_add_f32_dpp v67, v67, v67 quad_perm:[2,3,0,1] row_mask:0xf bank_mask:0xf bound_ctrl:1
	v_add_f32_dpp v68, v68, v68 quad_perm:[2,3,0,1] row_mask:0xf bank_mask:0xf bound_ctrl:1
	s_nop 0
	ds_read_b128 v[146:149], v83 offset:1024
	ds_read_b128 v[150:153], v83 offset:1040
	v_add_f32_dpp v67, v67, v67 row_half_mirror row_mask:0xf bank_mask:0xf bound_ctrl:1
	v_add_f32_dpp v68, v68, v68 row_half_mirror row_mask:0xf bank_mask:0xf bound_ctrl:1
	ds_read_b128 v[154:157], v83 offset:2048
	ds_read_b128 v[158:161], v83 offset:2064
	s_waitcnt lgkmcnt(12)
	v_mul_f32_e32 v69, v134, v67
	v_mul_f32_e32 v70, v135, v67
	v_mul_f32_e32 v80, v136, v67
	v_mul_f32_e32 v81, v137, v67
	s_waitcnt lgkmcnt(11)
	v_mul_f32_e32 v98, v62, v67
	v_mul_f32_e32 v99, v63, v67
	ds_read_b128 v[162:165], v83 offset:1792
	v_mul_f32_e32 v103, v64, v67
	ds_read_b128 v[178:181], v83 offset:1808
	v_mul_f32_e32 v67, v65, v67
	s_waitcnt lgkmcnt(12)
	v_fmac_f32_e32 v69, v46, v58
	v_fmac_f32_e32 v70, v47, v59
	v_fmac_f32_e32 v80, v48, v60
	v_fmac_f32_e32 v81, v49, v61
	s_waitcnt lgkmcnt(11)
	v_fmac_f32_e32 v98, v42, v54
	v_fmac_f32_e32 v99, v43, v55
	v_fmac_f32_e32 v103, v44, v56
	v_fmac_f32_e32 v67, v45, v57
	s_waitcnt lgkmcnt(9)
	v_fmac_f32_e32 v69, v50, v138
	v_fmac_f32_e32 v70, v50, v139
	v_fmac_f32_e32 v80, v50, v140
	v_fmac_f32_e32 v81, v50, v141
	s_waitcnt lgkmcnt(8)
	v_fmac_f32_e32 v98, v50, v142
	v_fmac_f32_e32 v99, v50, v143
	v_fmac_f32_e32 v103, v50, v144
	v_fmac_f32_e32 v67, v50, v145
	v_mul_f32_e32 v50, v134, v68
	v_fmac_f32_e32 v50, v38, v58
	v_mul_f32_e32 v121, v135, v68
	v_fmac_f32_e32 v50, v51, v138
	v_mul_f32_e32 v125, v136, v68
	v_mul_f32_e32 v138, v137, v68
	v_fmac_f32_e32 v121, v39, v59
	v_fmac_f32_e32 v125, v40, v60
	v_fmac_f32_e32 v138, v41, v61
	v_fmac_f32_e32 v121, v51, v139
	v_fmac_f32_e32 v125, v51, v140
	v_fmac_f32_e32 v138, v51, v141
	v_mul_f32_e32 v139, v62, v68
	v_mul_f32_e32 v140, v63, v68
	v_mul_f32_e32 v141, v64, v68
	v_mul_f32_e32 v68, v65, v68
	v_fmac_f32_e32 v139, v34, v54
	v_fmac_f32_e32 v140, v35, v55
	v_fmac_f32_e32 v141, v36, v56
	v_fmac_f32_e32 v68, v37, v57
	v_fmac_f32_e32 v139, v51, v142
	v_fmac_f32_e32 v140, v51, v143
	v_fmac_f32_e32 v141, v51, v144
	v_fmac_f32_e32 v68, v51, v145
	s_waitcnt lgkmcnt(7)
	v_mul_f32_e32 v51, v69, v126
	v_mul_f32_e32 v126, v50, v126
	s_nop 0
	v_fmac_f32_e32 v51, v70, v127
	v_fmac_f32_e32 v126, v121, v127
	v_fmac_f32_e32 v51, v80, v128
	ds_read_b128 v[62:65], v83 offset:2304
	ds_read_b128 v[34:37], v83 offset:2320
	v_fmac_f32_e32 v126, v125, v128
	v_fmac_f32_e32 v51, v81, v129
	v_fmac_f32_e32 v126, v138, v129
	ds_read_b128 v[46:49], v83 offset:3072
	s_waitcnt lgkmcnt(9)
	v_fmac_f32_e32 v51, v98, v130
	v_fmac_f32_e32 v126, v139, v130
	v_fmac_f32_e32 v51, v99, v131
	v_fmac_f32_e32 v126, v140, v131
	v_fmac_f32_e32 v51, v103, v132
	v_fmac_f32_e32 v126, v141, v132
	s_waitcnt lgkmcnt(8)
	v_mul_f32_e32 v95, v146, v69
	v_fmac_f32_e32 v51, v67, v133
	v_fmac_f32_e32 v126, v68, v133
	v_mul_f32_e32 v96, v146, v50
	v_fmac_f32_e32 v95, v70, v147
	s_nop 1
	s_nop 1
	s_nop 1
	v_add_f32_dpp v51, v51, v51 quad_perm:[1,0,3,2] row_mask:0xf bank_mask:0xf bound_ctrl:1
	v_add_f32_dpp v126, v126, v126 quad_perm:[1,0,3,2] row_mask:0xf bank_mask:0xf bound_ctrl:1
	ds_read_b128 v[38:41], v83 offset:3088
	s_nop 0
	v_add_f32_dpp v51, v51, v51 quad_perm:[2,3,0,1] row_mask:0xf bank_mask:0xf bound_ctrl:1
	v_add_f32_dpp v126, v126, v126 quad_perm:[2,3,0,1] row_mask:0xf bank_mask:0xf bound_ctrl:1
	s_nop 0
	v_add_f32_dpp v51, v51, v51 row_half_mirror row_mask:0xf bank_mask:0xf bound_ctrl:1
	v_add_f32_dpp v126, v126, v126 row_half_mirror row_mask:0xf bank_mask:0xf bound_ctrl:1
	v_fmac_f32_e32 v96, v121, v147
	s_waitcnt lgkmcnt(7)
	v_mul_f32_e32 v145, v155, v126
	v_fmac_f32_e32 v95, v80, v148
	v_fmac_f32_e32 v96, v125, v148
	s_waitcnt lgkmcnt(5)
	v_fmac_f32_e32 v145, v121, v163
	v_mul_f32_e32 v121, v156, v126
	v_fmac_f32_e32 v95, v81, v149
	v_fmac_f32_e32 v96, v138, v149
	v_mul_f32_e32 v142, v154, v51
	v_fmac_f32_e32 v121, v125, v164
	v_mul_f32_e32 v125, v157, v126
	ds_read_b128 v[54:57], v83 offset:3584
	ds_read_b128 v[58:61], v83 offset:3600
	v_fmac_f32_e32 v95, v98, v150
	v_fmac_f32_e32 v96, v139, v150
	v_fmac_f32_e32 v142, v69, v162
	v_mul_f32_e32 v69, v155, v51
	ds_read_b128 v[130:133], v83 offset:2560
	ds_read_b128 v[134:137], v83 offset:2576
	ds_read_b128 v[42:45], v83 offset:3328
	v_fmac_f32_e32 v125, v138, v165
	ds_read_b128 v[188:191], v83 offset:3344
	v_mul_f32_e32 v138, v158, v126
	v_fmac_f32_e32 v95, v99, v151
	v_fmac_f32_e32 v69, v70, v163
	v_mul_f32_e32 v70, v156, v51
	v_mul_f32_e32 v144, v160, v51
	s_waitcnt lgkmcnt(10)
	v_fmac_f32_e32 v138, v139, v178
	v_mul_f32_e32 v139, v159, v126
	v_fmac_f32_e32 v96, v140, v151
	v_fmac_f32_e32 v95, v103, v152
	v_fmac_f32_e32 v70, v80, v164
	v_mul_f32_e32 v80, v157, v51
	v_fmac_f32_e32 v144, v103, v180
	v_mul_f32_e32 v103, v161, v51
	v_fmac_f32_e32 v139, v140, v179
	v_mul_f32_e32 v140, v160, v126
	v_fmac_f32_e32 v96, v141, v152
	v_fmac_f32_e32 v95, v67, v153
	v_fmac_f32_e32 v80, v81, v165
	v_mul_f32_e32 v81, v158, v51
	v_mul_f32_e32 v143, v159, v51
	v_fmac_f32_e32 v103, v67, v181
	v_mul_f32_e32 v67, v154, v126
	v_fmac_f32_e32 v140, v141, v180
	v_mul_f32_e32 v141, v161, v126
	v_fmac_f32_e32 v81, v98, v178
	v_fmac_f32_e32 v143, v99, v179
	v_fmac_f32_e32 v67, v50, v162
	v_fmac_f32_e32 v141, v68, v181
	s_waitcnt lgkmcnt(9)
	v_fmac_f32_e32 v142, v52, v62
	v_fmac_f32_e32 v69, v52, v63
	v_fmac_f32_e32 v70, v52, v64
	ds_read2st64_b64 v[154:157], v66 offset0:8 offset1:11
	v_fmac_f32_e32 v80, v52, v65
	s_waitcnt lgkmcnt(9)
	v_fmac_f32_e32 v81, v52, v34
	v_fmac_f32_e32 v143, v52, v35
	v_fmac_f32_e32 v144, v52, v36
	ds_read_b128 v[148:151], v83 offset:3840
	ds_read_b128 v[126:129], v83 offset:3856
	v_fmac_f32_e32 v103, v52, v37
	v_fmac_f32_e32 v67, v53, v62
	v_fmac_f32_e32 v145, v53, v63
	v_fmac_f32_e32 v121, v53, v64
	v_fmac_f32_e32 v125, v53, v65
	v_fmac_f32_e32 v138, v53, v34
	v_fmac_f32_e32 v139, v53, v35
	v_fmac_f32_e32 v140, v53, v36
	v_fmac_f32_e32 v141, v53, v37
	v_fmac_f32_e32 v96, v68, v153
	s_nop 0
	s_waitcnt lgkmcnt(10)
	v_mul_f32_e32 v68, v142, v46
	v_mul_f32_e32 v46, v67, v46
	v_fmac_f32_e32 v68, v69, v47
	v_fmac_f32_e32 v46, v145, v47
	s_nop 0
	v_fmac_f32_e32 v68, v70, v48
	v_fmac_f32_e32 v46, v121, v48
	v_fmac_f32_e32 v68, v80, v49
	v_fmac_f32_e32 v46, v125, v49
	s_nop 0
	s_waitcnt lgkmcnt(9)
	v_fmac_f32_e32 v68, v81, v38
	v_fmac_f32_e32 v46, v138, v38
	v_fmac_f32_e32 v68, v143, v39
	v_fmac_f32_e32 v46, v139, v39
	v_fmac_f32_e32 v68, v144, v40
	v_fmac_f32_e32 v46, v140, v40
	v_fmac_f32_e32 v68, v103, v41
	v_fmac_f32_e32 v46, v141, v41
	s_nop 1
	s_nop 1
	ds_read_b128 v[34:37], v83 offset:4608
	ds_read_b128 v[38:41], v83 offset:4624
	s_nop 1
	v_add_f32_dpp v68, v68, v68 quad_perm:[1,0,3,2] row_mask:0xf bank_mask:0xf bound_ctrl:1
	v_add_f32_dpp v46, v46, v46 quad_perm:[1,0,3,2] row_mask:0xf bank_mask:0xf bound_ctrl:1
	s_nop 0
	v_add_f32_dpp v68, v68, v68 quad_perm:[2,3,0,1] row_mask:0xf bank_mask:0xf bound_ctrl:1
	v_add_f32_dpp v46, v46, v46 quad_perm:[2,3,0,1] row_mask:0xf bank_mask:0xf bound_ctrl:1
	s_nop 0
	v_add_f32_dpp v68, v68, v68 row_half_mirror row_mask:0xf bank_mask:0xf bound_ctrl:1
	v_add_f32_dpp v46, v46, v46 row_half_mirror row_mask:0xf bank_mask:0xf bound_ctrl:1
	s_waitcnt lgkmcnt(10)
	v_mul_f32_e32 v146, v54, v68
	s_waitcnt lgkmcnt(8)
	v_mul_f32_e32 v98, v130, v142
	s_waitcnt lgkmcnt(6)
	v_fmac_f32_e32 v146, v142, v42
	v_mul_f32_e32 v142, v55, v68
	v_fmac_f32_e32 v98, v69, v131
	v_fmac_f32_e32 v142, v69, v43
	v_mul_f32_e32 v69, v56, v68
	s_nop 0
	v_fmac_f32_e32 v98, v70, v132
	v_fmac_f32_e32 v69, v70, v44
	v_mul_f32_e32 v70, v57, v68
	v_fmac_f32_e32 v98, v80, v133
	v_fmac_f32_e32 v70, v80, v45
	v_mul_f32_e32 v80, v58, v68
	v_mul_f32_e32 v99, v130, v67
	ds_read_b128 v[62:65], v83 offset:5120
	ds_read_b128 v[158:161], v83 offset:5136
	v_fmac_f32_e32 v98, v81, v134
	ds_read_b128 v[162:165], v83 offset:4096
	v_fmac_f32_e32 v99, v145, v131
	ds_read_b128 v[50:53], v83 offset:4864
	s_waitcnt lgkmcnt(9)
	v_fmac_f32_e32 v80, v81, v188
	ds_read_b128 v[178:181], v83 offset:4880
	v_mul_f32_e32 v81, v59, v68
	v_fmac_f32_e32 v98, v143, v135
	v_fmac_f32_e32 v81, v143, v189
	v_mul_f32_e32 v143, v60, v68
	v_mul_f32_e32 v68, v61, v68
	v_fmac_f32_e32 v99, v121, v132
	v_fmac_f32_e32 v143, v144, v190
	v_fmac_f32_e32 v68, v103, v191
	v_fmac_f32_e32 v99, v125, v133
	s_waitcnt lgkmcnt(8)
	v_fmac_f32_e32 v146, v154, v148
	ds_read_b128 v[194:197], v83 offset:4112
	v_fmac_f32_e32 v142, v154, v149
	v_fmac_f32_e32 v69, v154, v150
	v_fmac_f32_e32 v70, v154, v151
	s_waitcnt lgkmcnt(8)
	v_fmac_f32_e32 v80, v154, v126
	v_fmac_f32_e32 v81, v154, v127
	v_fmac_f32_e32 v143, v154, v128
	v_fmac_f32_e32 v68, v154, v129
	v_mul_f32_e32 v154, v54, v46
	v_mul_f32_e32 v147, v58, v46
	v_fmac_f32_e32 v99, v138, v134
	v_fmac_f32_e32 v154, v67, v42
	v_mul_f32_e32 v67, v55, v46
	v_fmac_f32_e32 v147, v138, v188
	v_mul_f32_e32 v138, v59, v46
	v_fmac_f32_e32 v99, v139, v135
	v_fmac_f32_e32 v98, v144, v136
	v_fmac_f32_e32 v67, v145, v43
	v_mul_f32_e32 v144, v56, v46
	v_mul_f32_e32 v145, v57, v46
	v_fmac_f32_e32 v138, v139, v189
	v_mul_f32_e32 v139, v60, v46
	v_fmac_f32_e32 v99, v140, v136
	v_fmac_f32_e32 v144, v121, v44
	v_fmac_f32_e32 v145, v125, v45
	v_fmac_f32_e32 v139, v140, v190
	v_mul_f32_e32 v140, v61, v46
	v_fmac_f32_e32 v140, v141, v191
	v_fmac_f32_e32 v154, v155, v148
	v_fmac_f32_e32 v67, v155, v149
	v_fmac_f32_e32 v144, v155, v150
	v_fmac_f32_e32 v145, v155, v151
	v_fmac_f32_e32 v147, v155, v126
	v_fmac_f32_e32 v138, v155, v127
	v_fmac_f32_e32 v139, v155, v128
	v_fmac_f32_e32 v140, v155, v129
	s_waitcnt lgkmcnt(7)
	v_mul_f32_e32 v155, v146, v34
	v_mul_f32_e32 v34, v154, v34
	s_nop 0
	v_fmac_f32_e32 v155, v142, v35
	ds_read_b128 v[42:45], v83 offset:5376
	ds_read_b128 v[126:129], v83 offset:5392
	v_fmac_f32_e32 v34, v67, v35
	v_fmac_f32_e32 v155, v69, v36
	v_fmac_f32_e32 v34, v144, v36
	ds_read_b128 v[46:49], v83 offset:6144
	ds_read_b128 v[188:191], v83 offset:6160
	v_fmac_f32_e32 v155, v70, v37
	v_fmac_f32_e32 v34, v145, v37
	s_waitcnt lgkmcnt(10)
	v_fmac_f32_e32 v155, v80, v38
	v_fmac_f32_e32 v34, v147, v38
	s_nop 0
	v_fmac_f32_e32 v155, v81, v39
	v_fmac_f32_e32 v34, v138, v39
	v_fmac_f32_e32 v155, v143, v40
	v_fmac_f32_e32 v34, v139, v40
	v_fmac_f32_e32 v155, v68, v41
	v_fmac_f32_e32 v34, v140, v41
	v_fmac_f32_e32 v99, v141, v137
	s_nop 1
	s_nop 1
	s_nop 1
	v_add_f32_dpp v155, v155, v155 quad_perm:[1,0,3,2] row_mask:0xf bank_mask:0xf bound_ctrl:1
	v_add_f32_dpp v34, v34, v34 quad_perm:[1,0,3,2] row_mask:0xf bank_mask:0xf bound_ctrl:1
	s_nop 0
	v_add_f32_dpp v155, v155, v155 quad_perm:[2,3,0,1] row_mask:0xf bank_mask:0xf bound_ctrl:1
	v_add_f32_dpp v34, v34, v34 quad_perm:[2,3,0,1] row_mask:0xf bank_mask:0xf bound_ctrl:1
	s_nop 0
	v_add_f32_dpp v155, v155, v155 row_half_mirror row_mask:0xf bank_mask:0xf bound_ctrl:1
	v_add_f32_dpp v34, v34, v34 row_half_mirror row_mask:0xf bank_mask:0xf bound_ctrl:1
	v_fmac_f32_e32 v98, v103, v137
	s_waitcnt lgkmcnt(9)
	v_mul_f32_e32 v141, v62, v155
	s_waitcnt lgkmcnt(7)
	v_mul_f32_e32 v103, v162, v146
	s_waitcnt lgkmcnt(6)
	v_fmac_f32_e32 v141, v146, v50
	v_mul_f32_e32 v146, v63, v155
	v_fmac_f32_e32 v103, v142, v163
	v_fmac_f32_e32 v146, v142, v51
	v_mul_f32_e32 v142, v64, v155
	s_nop 0
	v_fmac_f32_e32 v103, v69, v164
	v_fmac_f32_e32 v142, v69, v52
	v_mul_f32_e32 v69, v65, v155
	v_fmac_f32_e32 v103, v70, v165
	v_fmac_f32_e32 v69, v70, v53
	v_mul_f32_e32 v70, v158, v155
	ds_read_b128 v[130:133], v83 offset:5632
	ds_read_b128 v[54:57], v83 offset:6656
	ds_read_b128 v[58:61], v83 offset:6672
	v_mul_f32_e32 v121, v162, v154
	s_waitcnt lgkmcnt(7)
	v_fmac_f32_e32 v103, v80, v194
	ds_read_b128 v[134:137], v83 offset:5648
	v_mul_f32_e32 v148, v63, v34
	ds_read_b128 v[202:205], v83 offset:6400
	ds_read_b128 v[38:41], v83 offset:6416
	v_fmac_f32_e32 v70, v80, v178
	v_mul_f32_e32 v80, v159, v155
	v_fmac_f32_e32 v121, v67, v163
	v_fmac_f32_e32 v103, v81, v195
	v_fmac_f32_e32 v148, v67, v51
	v_fmac_f32_e32 v80, v81, v179
	v_mul_f32_e32 v81, v160, v155
	v_mul_f32_e32 v67, v64, v34
	v_fmac_f32_e32 v121, v144, v164
	v_fmac_f32_e32 v103, v143, v196
	v_fmac_f32_e32 v67, v144, v52
	v_fmac_f32_e32 v81, v143, v180
	v_mul_f32_e32 v143, v161, v155
	v_mul_f32_e32 v144, v65, v34
	v_fmac_f32_e32 v121, v145, v165
	v_fmac_f32_e32 v103, v68, v197
	v_fmac_f32_e32 v144, v145, v53
	v_fmac_f32_e32 v143, v68, v181
	v_mul_f32_e32 v68, v62, v34
	v_mul_f32_e32 v145, v158, v34
	v_fmac_f32_e32 v121, v147, v194
	v_fmac_f32_e32 v68, v154, v50
	v_fmac_f32_e32 v145, v147, v178
	v_mul_f32_e32 v147, v159, v34
	v_fmac_f32_e32 v147, v138, v179
	s_waitcnt lgkmcnt(9)
	v_fmac_f32_e32 v141, v156, v42
	v_fmac_f32_e32 v68, v157, v42
	s_waitcnt lgkmcnt(8)
	v_fmac_f32_e32 v80, v156, v127
	v_fmac_f32_e32 v146, v156, v43
	v_fmac_f32_e32 v148, v157, v43
	v_fmac_f32_e32 v147, v157, v127
	s_waitcnt lgkmcnt(7)
	v_mul_f32_e32 v127, v141, v46
	v_mul_f32_e32 v46, v68, v46
	ds_read2st64_b64 v[162:165], v66 offset0:14 offset1:17
	s_nop 0
	v_fmac_f32_e32 v142, v156, v44
	v_fmac_f32_e32 v67, v157, v44
	v_fmac_f32_e32 v127, v146, v47
	ds_read_b128 v[62:65], v83 offset:6912
	ds_read_b128 v[50:53], v83 offset:6928
	v_fmac_f32_e32 v46, v148, v47
	v_fmac_f32_e32 v69, v156, v45
	v_fmac_f32_e32 v144, v157, v45
	v_fmac_f32_e32 v127, v142, v48
	v_fmac_f32_e32 v46, v67, v48
	v_mul_f32_e32 v149, v160, v34
	v_fmac_f32_e32 v70, v156, v126
	v_fmac_f32_e32 v145, v157, v126
	v_fmac_f32_e32 v149, v139, v180
	v_fmac_f32_e32 v127, v69, v49
	v_fmac_f32_e32 v46, v144, v49
	v_mul_f32_e32 v150, v161, v34
	v_fmac_f32_e32 v150, v140, v181
	s_waitcnt lgkmcnt(9)
	v_fmac_f32_e32 v127, v70, v188
	v_fmac_f32_e32 v46, v145, v188
	v_fmac_f32_e32 v81, v156, v128
	v_fmac_f32_e32 v149, v157, v128
	v_fmac_f32_e32 v121, v138, v195
	v_fmac_f32_e32 v127, v80, v189
	v_fmac_f32_e32 v46, v147, v189
	v_fmac_f32_e32 v121, v139, v196
	v_fmac_f32_e32 v143, v156, v129
	v_fmac_f32_e32 v150, v157, v129
	v_fmac_f32_e32 v127, v81, v190
	v_fmac_f32_e32 v46, v149, v190
	v_fmac_f32_e32 v127, v143, v191
	v_fmac_f32_e32 v46, v150, v191
	ds_read_b128 v[42:45], v83 offset:7680
	ds_read_b128 v[34:37], v83 offset:7696
	v_fmac_f32_e32 v121, v140, v197
	s_nop 1
	s_waitcnt lgkmcnt(10)
	v_mul_f32_e32 v125, v130, v141
	s_nop 1
	v_add_f32_dpp v127, v127, v127 quad_perm:[1,0,3,2] row_mask:0xf bank_mask:0xf bound_ctrl:1
	v_add_f32_dpp v46, v46, v46 quad_perm:[1,0,3,2] row_mask:0xf bank_mask:0xf bound_ctrl:1
	s_nop 0
	v_add_f32_dpp v127, v127, v127 quad_perm:[2,3,0,1] row_mask:0xf bank_mask:0xf bound_ctrl:1
	v_add_f32_dpp v46, v46, v46 quad_perm:[2,3,0,1] row_mask:0xf bank_mask:0xf bound_ctrl:1
	s_nop 0
	v_add_f32_dpp v127, v127, v127 row_half_mirror row_mask:0xf bank_mask:0xf bound_ctrl:1
	v_add_f32_dpp v46, v46, v46 row_half_mirror row_mask:0xf bank_mask:0xf bound_ctrl:1
	s_waitcnt lgkmcnt(9)
	v_mul_f32_e32 v152, v55, v127
	v_fmac_f32_e32 v125, v146, v131
	s_waitcnt lgkmcnt(6)
	v_fmac_f32_e32 v152, v146, v203
	v_mul_f32_e32 v146, v56, v127
	v_fmac_f32_e32 v125, v142, v132
	v_fmac_f32_e32 v146, v142, v204
	v_mul_f32_e32 v142, v57, v127
	v_fmac_f32_e32 v125, v69, v133
	ds_read_b128 v[154:157], v83 offset:7168
	v_fmac_f32_e32 v142, v69, v205
	v_mul_f32_e32 v69, v58, v127
	v_fmac_f32_e32 v125, v70, v134
	s_waitcnt lgkmcnt(6)
	v_fmac_f32_e32 v69, v70, v38
	v_mul_f32_e32 v70, v59, v127
	v_mul_f32_e32 v126, v130, v68
	v_fmac_f32_e32 v125, v80, v135
	v_fmac_f32_e32 v70, v80, v39
	v_mul_f32_e32 v80, v60, v127
	v_fmac_f32_e32 v125, v81, v136
	v_fmac_f32_e32 v126, v148, v131
	v_fmac_f32_e32 v80, v81, v40
	v_mul_f32_e32 v81, v61, v127
	v_fmac_f32_e32 v125, v143, v137
	v_mul_f32_e32 v151, v54, v127
	v_fmac_f32_e32 v81, v143, v41
	v_mul_f32_e32 v143, v56, v46
	v_fmac_f32_e32 v126, v67, v132
	v_fmac_f32_e32 v151, v141, v202
	v_fmac_f32_e32 v143, v67, v204
	v_mul_f32_e32 v67, v57, v46
	v_fmac_f32_e32 v126, v144, v133
	s_waitcnt lgkmcnt(4)
	v_fmac_f32_e32 v151, v162, v62
	v_fmac_f32_e32 v152, v162, v63
	v_fmac_f32_e32 v146, v162, v64
	v_fmac_f32_e32 v142, v162, v65
	s_waitcnt lgkmcnt(3)
	v_fmac_f32_e32 v69, v162, v50
	v_fmac_f32_e32 v70, v162, v51
	v_fmac_f32_e32 v80, v162, v52
	v_fmac_f32_e32 v81, v162, v53
	v_mul_f32_e32 v162, v54, v46
	v_fmac_f32_e32 v67, v144, v205
	v_mul_f32_e32 v144, v58, v46
	v_fmac_f32_e32 v126, v145, v134
	v_fmac_f32_e32 v162, v68, v202
	v_mul_f32_e32 v68, v55, v46
	v_fmac_f32_e32 v144, v145, v38
	v_mul_f32_e32 v145, v59, v46
	v_fmac_f32_e32 v126, v147, v135
	v_fmac_f32_e32 v68, v148, v203
	v_fmac_f32_e32 v145, v147, v39
	v_mul_f32_e32 v147, v60, v46
	v_mul_f32_e32 v148, v61, v46
	v_fmac_f32_e32 v147, v149, v40
	v_fmac_f32_e32 v162, v163, v62
	v_fmac_f32_e32 v148, v150, v41
	v_fmac_f32_e32 v68, v163, v63
	v_fmac_f32_e32 v143, v163, v64
	v_fmac_f32_e32 v67, v163, v65
	v_fmac_f32_e32 v144, v163, v50
	v_fmac_f32_e32 v145, v163, v51
	v_fmac_f32_e32 v147, v163, v52
	v_fmac_f32_e32 v148, v163, v53
	s_waitcnt lgkmcnt(2)
	v_mul_f32_e32 v163, v151, v42
	v_mul_f32_e32 v42, v162, v42
	s_nop 0
	v_fmac_f32_e32 v163, v152, v43
	v_fmac_f32_e32 v42, v68, v43
	v_fmac_f32_e32 v163, v146, v44
	v_fmac_f32_e32 v42, v143, v44
	v_fmac_f32_e32 v126, v149, v136
	v_fmac_f32_e32 v163, v142, v45
	v_fmac_f32_e32 v42, v67, v45
	s_waitcnt lgkmcnt(1)
	v_fmac_f32_e32 v163, v69, v34
	v_fmac_f32_e32 v42, v144, v34
	v_fmac_f32_e32 v126, v150, v137
	ds_read_b128 v[136:139], v83 offset:7184
	ds_read_b128 v[54:57], v83 offset:8192
	ds_read_b128 v[58:61], v83 offset:8208
	ds_read_b128 v[50:53], v83 offset:7936
	ds_read_b128 v[38:41], v83 offset:7952
	ds_read_b128 v[62:65], v83 offset:8448
	ds_read_b128 v[130:133], v83 offset:8464
	ds_read_b128 v[46:49], v83 offset:9216
	v_fmac_f32_e32 v163, v70, v35
	v_fmac_f32_e32 v42, v145, v35
	ds_read_b128 v[158:161], v83 offset:9232
	s_nop 0
	s_waitcnt lgkmcnt(9)
	v_mul_f32_e32 v127, v154, v151
	v_fmac_f32_e32 v163, v80, v36
	v_fmac_f32_e32 v42, v147, v36
	v_fmac_f32_e32 v127, v152, v155
	v_fmac_f32_e32 v163, v81, v37
	v_fmac_f32_e32 v42, v148, v37
	v_mul_f32_e32 v128, v154, v162
	v_fmac_f32_e32 v127, v146, v156
	s_nop 1
	s_nop 1
	s_nop 1
	v_add_f32_dpp v163, v163, v163 quad_perm:[1,0,3,2] row_mask:0xf bank_mask:0xf bound_ctrl:1
	v_add_f32_dpp v42, v42, v42 quad_perm:[1,0,3,2] row_mask:0xf bank_mask:0xf bound_ctrl:1
	ds_read2st64_b64 v[34:37], v66 offset0:20 offset1:23
	s_nop 0
	v_add_f32_dpp v163, v163, v163 quad_perm:[2,3,0,1] row_mask:0xf bank_mask:0xf bound_ctrl:1
	ds_read_b128 v[178:181], v83 offset:8704
	v_add_f32_dpp v42, v42, v42 quad_perm:[2,3,0,1] row_mask:0xf bank_mask:0xf bound_ctrl:1
	s_nop 0
	v_add_f32_dpp v163, v163, v163 row_half_mirror row_mask:0xf bank_mask:0xf bound_ctrl:1
	v_add_f32_dpp v42, v42, v42 row_half_mirror row_mask:0xf bank_mask:0xf bound_ctrl:1
	v_fmac_f32_e32 v128, v68, v155
	s_waitcnt lgkmcnt(9)
	v_mul_f32_e32 v150, v55, v163
	v_fmac_f32_e32 v127, v142, v157
	ds_read_b128 v[188:191], v83 offset:8720
	v_fmac_f32_e32 v128, v143, v156
	s_waitcnt lgkmcnt(8)
	v_fmac_f32_e32 v150, v152, v51
	v_mul_f32_e32 v152, v58, v163
	v_fmac_f32_e32 v127, v69, v136
	v_fmac_f32_e32 v128, v67, v157
	s_waitcnt lgkmcnt(7)
	v_fmac_f32_e32 v152, v69, v38
	v_mul_f32_e32 v69, v59, v163
	v_mul_f32_e32 v154, v57, v42
	v_fmac_f32_e32 v127, v70, v137
	v_fmac_f32_e32 v128, v144, v136
	v_fmac_f32_e32 v69, v70, v39
	ds_read_b128 v[194:197], v83 offset:9728
	ds_read_b128 v[202:205], v83 offset:9744
	v_mul_f32_e32 v70, v60, v163
	v_fmac_f32_e32 v154, v67, v53
	v_mul_f32_e32 v67, v58, v42
	v_fmac_f32_e32 v127, v80, v138
	v_fmac_f32_e32 v67, v144, v38
	ds_read_b128 v[206:209], v83 offset:9472
	ds_read_b128 v[212:215], v83 offset:9488
	v_mul_f32_e32 v149, v54, v163
	v_fmac_f32_e32 v70, v80, v40
	v_mul_f32_e32 v80, v61, v163
	v_mul_f32_e32 v144, v59, v42
	v_fmac_f32_e32 v128, v145, v137
	v_fmac_f32_e32 v127, v81, v139
	v_mul_f32_e32 v153, v55, v42
	v_fmac_f32_e32 v149, v151, v50
	v_mul_f32_e32 v151, v56, v163
	v_fmac_f32_e32 v80, v81, v41
	v_mul_f32_e32 v81, v54, v42
	v_fmac_f32_e32 v144, v145, v39
	v_mul_f32_e32 v145, v60, v42
	v_fmac_f32_e32 v128, v147, v138
	v_fmac_f32_e32 v151, v146, v52
	v_mul_f32_e32 v146, v57, v163
	v_fmac_f32_e32 v81, v162, v50
	v_fmac_f32_e32 v153, v68, v51
	v_mul_f32_e32 v68, v56, v42
	v_fmac_f32_e32 v145, v147, v40
	v_mul_f32_e32 v147, v61, v42
	v_fmac_f32_e32 v146, v142, v53
	s_waitcnt lgkmcnt(10)
	v_fmac_f32_e32 v149, v164, v62
	v_fmac_f32_e32 v81, v165, v62
	v_fmac_f32_e32 v68, v143, v52
	v_fmac_f32_e32 v147, v148, v41
	s_nop 0
	ds_read_b128 v[38:41], v83 offset:9984
	ds_read_b128 v[54:57], v83 offset:10000
	v_fmac_f32_e32 v150, v164, v63
	v_fmac_f32_e32 v151, v164, v64
	v_fmac_f32_e32 v146, v164, v65
	s_waitcnt lgkmcnt(11)
	v_fmac_f32_e32 v152, v164, v130
	v_fmac_f32_e32 v69, v164, v131
	v_fmac_f32_e32 v70, v164, v132
	v_fmac_f32_e32 v80, v164, v133
	v_fmac_f32_e32 v153, v165, v63
	v_fmac_f32_e32 v68, v165, v64
	v_fmac_f32_e32 v154, v165, v65
	v_fmac_f32_e32 v67, v165, v130
	v_fmac_f32_e32 v144, v165, v131
	v_fmac_f32_e32 v145, v165, v132
	v_fmac_f32_e32 v147, v165, v133
	s_waitcnt lgkmcnt(10)
	v_mul_f32_e32 v66, v149, v46
	v_mul_f32_e32 v46, v81, v46
	v_fmac_f32_e32 v66, v150, v47
	v_fmac_f32_e32 v46, v153, v47
	v_fmac_f32_e32 v66, v151, v48
	v_fmac_f32_e32 v46, v68, v48
	v_fmac_f32_e32 v128, v148, v139
	v_fmac_f32_e32 v66, v146, v49
	v_fmac_f32_e32 v46, v154, v49
	s_nop 0
	s_waitcnt lgkmcnt(7)
	v_mul_f32_e32 v129, v178, v149
	v_fmac_f32_e32 v66, v152, v158
	v_fmac_f32_e32 v46, v67, v158
	v_fmac_f32_e32 v129, v150, v179
	s_nop 0
	v_fmac_f32_e32 v66, v69, v159
	v_fmac_f32_e32 v46, v144, v159
	v_fmac_f32_e32 v129, v151, v180
	v_fmac_f32_e32 v66, v70, v160
	v_fmac_f32_e32 v46, v145, v160
	v_fmac_f32_e32 v129, v146, v181
	ds_read_b128 v[42:45], v83 offset:10752
	ds_read_b128 v[132:135], v83 offset:10768
	v_fmac_f32_e32 v66, v80, v161
	v_fmac_f32_e32 v46, v147, v161
	v_mul_f32_e32 v130, v178, v81
	s_waitcnt lgkmcnt(8)
	v_fmac_f32_e32 v129, v152, v188
	s_nop 1
	s_nop 1
	v_add_f32_dpp v66, v66, v66 quad_perm:[1,0,3,2] row_mask:0xf bank_mask:0xf bound_ctrl:1
	v_add_f32_dpp v46, v46, v46 quad_perm:[1,0,3,2] row_mask:0xf bank_mask:0xf bound_ctrl:1
	s_nop 0
	v_add_f32_dpp v66, v66, v66 quad_perm:[2,3,0,1] row_mask:0xf bank_mask:0xf bound_ctrl:1
	v_add_f32_dpp v46, v46, v46 quad_perm:[2,3,0,1] row_mask:0xf bank_mask:0xf bound_ctrl:1
	s_nop 0
	v_add_f32_dpp v66, v66, v66 row_half_mirror row_mask:0xf bank_mask:0xf bound_ctrl:1
	v_add_f32_dpp v46, v46, v46 row_half_mirror row_mask:0xf bank_mask:0xf bound_ctrl:1
	v_fmac_f32_e32 v130, v153, v179
	s_waitcnt lgkmcnt(7)
	v_mul_f32_e32 v50, v194, v66
	v_fmac_f32_e32 v129, v69, v189
	v_fmac_f32_e32 v130, v68, v180
	s_waitcnt lgkmcnt(5)
	v_fmac_f32_e32 v50, v149, v206
	v_mul_f32_e32 v53, v197, v66
	v_mul_f32_e32 v149, v204, v66
	v_fmac_f32_e32 v129, v70, v190
	ds_read_b128 v[136:139], v83 offset:10240
	ds_read_b128 v[140:143], v83 offset:10256
	v_fmac_f32_e32 v53, v146, v209
	ds_read_b128 v[58:61], v83 offset:11264
	ds_read_b128 v[62:65], v83 offset:11280
	v_mul_f32_e32 v51, v195, v66
	v_mul_f32_e32 v52, v196, v66
	v_mul_f32_e32 v146, v202, v66
	v_mul_f32_e32 v148, v203, v66
	s_waitcnt lgkmcnt(8)
	v_fmac_f32_e32 v149, v70, v214
	v_mul_f32_e32 v70, v205, v66
	v_fmac_f32_e32 v130, v154, v181
	v_fmac_f32_e32 v51, v150, v207
	v_fmac_f32_e32 v52, v151, v208
	v_fmac_f32_e32 v146, v152, v212
	v_fmac_f32_e32 v148, v69, v213
	v_fmac_f32_e32 v70, v80, v215
	v_fmac_f32_e32 v130, v67, v188
	v_fmac_f32_e32 v129, v80, v191
	s_waitcnt lgkmcnt(7)
	v_fmac_f32_e32 v50, v34, v38
	v_fmac_f32_e32 v51, v34, v39
	v_fmac_f32_e32 v52, v34, v40
	v_fmac_f32_e32 v53, v34, v41
	s_waitcnt lgkmcnt(6)
	v_fmac_f32_e32 v146, v34, v54
	v_fmac_f32_e32 v148, v34, v55
	v_fmac_f32_e32 v149, v34, v56
	v_fmac_f32_e32 v70, v34, v57
	v_mul_f32_e32 v34, v194, v46
	v_mul_f32_e32 v80, v195, v46
	v_mul_f32_e32 v150, v197, v46
	v_fmac_f32_e32 v130, v144, v189
	v_fmac_f32_e32 v34, v81, v206
	v_fmac_f32_e32 v80, v153, v207
	v_mul_f32_e32 v81, v196, v46
	v_fmac_f32_e32 v150, v154, v209
	v_mul_f32_e32 v151, v202, v46
	v_mul_f32_e32 v152, v203, v46
	v_mul_f32_e32 v153, v204, v46
	v_mul_f32_e32 v154, v205, v46
	v_fmac_f32_e32 v130, v145, v190
	v_fmac_f32_e32 v81, v68, v208
	v_fmac_f32_e32 v34, v35, v38
	v_fmac_f32_e32 v151, v67, v212
	v_fmac_f32_e32 v152, v144, v213
	v_fmac_f32_e32 v153, v145, v214
	v_fmac_f32_e32 v154, v147, v215
	v_fmac_f32_e32 v130, v147, v191
	v_fmac_f32_e32 v80, v35, v39
	v_fmac_f32_e32 v81, v35, v40
	v_fmac_f32_e32 v150, v35, v41
	v_fmac_f32_e32 v151, v35, v54
	v_fmac_f32_e32 v152, v35, v55
	v_fmac_f32_e32 v153, v35, v56
	v_fmac_f32_e32 v154, v35, v57
	ds_read_b128 v[54:57], v83 offset:11008
	ds_read_b128 v[38:41], v83 offset:11024
	ds_read_b128 v[66:69], v83 offset:11520
	ds_read_b128 v[156:159], v83 offset:11536
	s_nop 0
	s_waitcnt lgkmcnt(9)
	v_mul_f32_e32 v35, v50, v42
	v_mul_f32_e32 v147, v34, v42
	v_fmac_f32_e32 v35, v51, v43
	v_fmac_f32_e32 v147, v80, v43
	s_nop 0
	v_fmac_f32_e32 v35, v52, v44
	v_fmac_f32_e32 v147, v81, v44
	v_fmac_f32_e32 v35, v53, v45
	v_fmac_f32_e32 v147, v150, v45
	s_nop 0
	s_waitcnt lgkmcnt(8)
	v_fmac_f32_e32 v35, v146, v132
	v_fmac_f32_e32 v147, v151, v132
	v_fmac_f32_e32 v35, v148, v133
	v_fmac_f32_e32 v147, v152, v133
	v_fmac_f32_e32 v35, v149, v134
	v_fmac_f32_e32 v147, v153, v134
	v_fmac_f32_e32 v35, v70, v135
	v_fmac_f32_e32 v147, v154, v135
	s_nop 1
	s_waitcnt lgkmcnt(7)
	v_mul_f32_e32 v131, v136, v50
	s_nop 1
	v_add_f32_dpp v35, v35, v35 quad_perm:[1,0,3,2] row_mask:0xf bank_mask:0xf bound_ctrl:1
	v_add_f32_dpp v147, v147, v147 quad_perm:[1,0,3,2] row_mask:0xf bank_mask:0xf bound_ctrl:1
	s_nop 0
	v_add_f32_dpp v35, v35, v35 quad_perm:[2,3,0,1] row_mask:0xf bank_mask:0xf bound_ctrl:1
	v_add_f32_dpp v147, v147, v147 quad_perm:[2,3,0,1] row_mask:0xf bank_mask:0xf bound_ctrl:1
	s_nop 0
	v_add_f32_dpp v35, v35, v35 row_half_mirror row_mask:0xf bank_mask:0xf bound_ctrl:1
	v_add_f32_dpp v147, v147, v147 row_half_mirror row_mask:0xf bank_mask:0xf bound_ctrl:1
	v_mul_f32_e32 v132, v136, v34
	s_waitcnt lgkmcnt(5)
	v_mul_f32_e32 v42, v58, v35
	v_mul_f32_e32 v43, v59, v35
	v_fmac_f32_e32 v131, v51, v137
	s_nop 0
	s_waitcnt lgkmcnt(3)
	v_fmac_f32_e32 v42, v50, v54
	v_fmac_f32_e32 v43, v51, v55
	v_mul_f32_e32 v44, v60, v35
	v_mul_f32_e32 v45, v61, v35
	v_mul_f32_e32 v48, v62, v35
	v_mul_f32_e32 v49, v63, v35
	v_mul_f32_e32 v50, v64, v35
	v_mul_f32_e32 v51, v65, v35
	v_fmac_f32_e32 v132, v80, v137
	v_fmac_f32_e32 v44, v52, v56
	v_fmac_f32_e32 v45, v53, v57
	s_waitcnt lgkmcnt(2)
	v_fmac_f32_e32 v48, v146, v38
	v_fmac_f32_e32 v49, v148, v39
	v_fmac_f32_e32 v50, v149, v40
	v_fmac_f32_e32 v51, v70, v41
	s_waitcnt lgkmcnt(1)
	v_fmac_f32_e32 v42, v36, v66
	v_fmac_f32_e32 v43, v36, v67
	v_fmac_f32_e32 v44, v36, v68
	v_fmac_f32_e32 v45, v36, v69
	s_waitcnt lgkmcnt(0)
	v_fmac_f32_e32 v48, v36, v156
	v_fmac_f32_e32 v49, v36, v157
	v_fmac_f32_e32 v50, v36, v158
	v_fmac_f32_e32 v51, v36, v159
	s_waitcnt vmcnt(7)
	v_cvt_f32_f16_e32 v36, v123
	s_add_i32 s91, s52, 1
	v_fmac_f32_e32 v131, v52, v138
	v_fmac_f32_e32 v131, v53, v139
	v_mul_f32_e32 v53, v59, v147
	v_mul_f32_e32 v59, v65, v147
	v_fmac_f32_e32 v59, v154, v41
	v_mul_f32_e32 v41, v102, v36
	v_mul_f32_e32 v46, v41, v41
	v_fmac_f32_e32 v53, v80, v55
	v_mul_f32_e32 v55, v61, v147
	v_mov_b32_dpp v46, v46 quad_perm:[1,0,3,2] row_mask:0xf bank_mask:0xf bound_ctrl:1
	v_fmac_f32_e32 v46, v41, v41
	v_fmac_f32_e32 v55, v150, v57
	v_mul_f32_e32 v57, v63, v147
	ds_read_b128 v[160:163], v83 offset:11776
	ds_read_b128 v[164:167], v83 offset:11792
	v_add_f32_dpp v46, v46, v46 quad_perm:[2,3,0,1] row_mask:0xf bank_mask:0xf bound_ctrl:1
	v_mul_f32_e32 v52, v58, v147
	v_fmac_f32_e32 v57, v152, v39
	v_mul_f32_e32 v58, v64, v147
	v_cvt_f32_f16_e32 v35, v109
	v_cvt_f32_ubyte0_e32 v39, v116
	v_add_f32_dpp v46, v46, v46 row_half_mirror row_mask:0xf bank_mask:0xf bound_ctrl:1
	v_fmac_f32_e32 v58, v153, v40
	s_bitcmp1_b32 s91, 0
	v_mul_f32_e32 v40, 0x3b808081, v39
	v_add_f32_dpp v46, v46, v46 row_mirror row_mask:0xf bank_mask:0xf bound_ctrl:1
	v_fma_f32 v39, v39, s45, -1.0
	s_cselect_b32 s10, 0x6000, 0
	v_readlane_b32 s11, v46, 16
	v_readlane_b32 s13, v46, 48
	v_fma_f32 v39, v39, v101, 1.0
	v_fmac_f32_e32 v52, v34, v54
	v_mul_f32_e32 v54, v60, v147
	v_add_u32_e32 v34, s10, v1
	v_readlane_b32 s10, v46, 0
	v_readlane_b32 s12, v46, 32
	v_mov_b32_e32 v46, s11
	v_mov_b32_e32 v47, s13
	v_mul_f32_e32 v36, v39, v36
	v_fmac_f32_e32 v54, v81, v56
	v_mul_f32_e32 v56, v62, v147
	v_add_f32_e32 v46, s10, v46
	v_add_f32_e32 v47, s12, v47
	v_mul_f32_e32 v39, v36, v35
	v_fmac_f32_e32 v56, v151, v38
	v_cvt_f32_ubyte0_e32 v38, v115
	v_add_f32_e32 v46, v46, v47
	v_mul_f32_e32 v47, v100, v39
	v_add_f32_e32 v46, 0x2b8cbccc, v46
	v_mul_f32_e32 v38, 0xbb1be179, v38
	v_mov_b32_dpp v47, v47 quad_perm:[1,0,3,2] row_mask:0xf bank_mask:0xf bound_ctrl:1
	v_fmac_f32_e32 v132, v81, v138
	v_rsq_f32_e32 v46, v46
	v_fmac_f32_e32 v47, v100, v39
	v_mul_f32_e32 v38, 0x3fb8aa3b, v38
	v_fmac_f32_e32 v132, v150, v139
	v_add_f32_dpp v39, v47, v47 quad_perm:[2,3,0,1] row_mask:0xf bank_mask:0xf bound_ctrl:1
	v_exp_f32_e32 v38, v38
	s_nop 0
	v_add_f32_dpp v39, v39, v39 row_half_mirror row_mask:0xf bank_mask:0xf bound_ctrl:1
	v_fmac_f32_e32 v131, v146, v140
	v_fmac_f32_e32 v132, v151, v140
	v_fmac_f32_e32 v131, v148, v141
	v_fmac_f32_e32 v132, v152, v141
	v_fmac_f32_e32 v52, v37, v66
	v_fmac_f32_e32 v53, v37, v67
	v_fmac_f32_e32 v54, v37, v68
	v_fmac_f32_e32 v55, v37, v69
	v_fmac_f32_e32 v56, v37, v156
	v_fmac_f32_e32 v57, v37, v157
	v_fmac_f32_e32 v58, v37, v158
	v_fmac_f32_e32 v59, v37, v159
	s_waitcnt vmcnt(6)
	v_cvt_f32_f16_e32 v37, v124
	v_add_f32_dpp v39, v39, v39 row_mirror row_mask:0xf bank_mask:0xf bound_ctrl:1
	v_fmac_f32_e32 v131, v149, v142
	v_fmac_f32_e32 v132, v153, v142
	v_readlane_b32 s14, v39, 0
	v_readlane_b32 s16, v39, 16
	v_readlane_b32 s15, v39, 32
	v_readlane_b32 s17, v39, 48
	v_add_u32_e32 v39, s48, v34
	v_mul_f32_e64 v41, v41, -v46
	v_fmac_f32_e32 v131, v70, v143
	v_fmac_f32_e32 v132, v154, v143
	ds_write2st64_b32 v39, v41, v38 offset1:1
	v_mul_f32_e64 v38, v40, -v41
	ds_write2st64_b32 v39, v38, v36 offset0:2 offset1:3
	ds_write2st64_b32 v39, v35, v37 offset0:4 offset1:5
	s_waitcnt vmcnt(5)
	v_cvt_f32_f16_e32 v36, v117
	v_cvt_f32_f16_e32 v35, v105
	v_cvt_f32_ubyte0_e32 v39, v114
	v_mul_f32_e32 v40, 0x3b808081, v39
	v_mul_f32_e32 v41, v102, v36
	v_mul_f32_e32 v46, v41, v41
	v_fma_f32 v39, v39, s45, -1.0
	v_fma_f32 v39, v39, v101, 1.0
	v_mov_b32_dpp v46, v46 quad_perm:[1,0,3,2] row_mask:0xf bank_mask:0xf bound_ctrl:1
	v_fmac_f32_e32 v46, v41, v41
	v_mul_f32_e32 v36, v39, v36
	v_mul_f32_e32 v39, v36, v35
	v_add_f32_dpp v46, v46, v46 quad_perm:[2,3,0,1] row_mask:0xf bank_mask:0xf bound_ctrl:1
	v_cvt_f32_ubyte0_e32 v38, v113
	v_mul_f32_e32 v38, 0xbb1be179, v38
	v_add_f32_dpp v46, v46, v46 row_half_mirror row_mask:0xf bank_mask:0xf bound_ctrl:1
	v_mul_f32_e32 v38, 0x3fb8aa3b, v38
	v_exp_f32_e32 v38, v38
	v_add_f32_dpp v46, v46, v46 row_mirror row_mask:0xf bank_mask:0xf bound_ctrl:1
	s_waitcnt vmcnt(4)
	v_cvt_f32_f16_e32 v37, v118
	v_readlane_b32 s11, v46, 16
	v_readlane_b32 s13, v46, 48
	v_readlane_b32 s10, v46, 0
	v_readlane_b32 s12, v46, 32
	v_mov_b32_e32 v46, s11
	v_mov_b32_e32 v47, s13
	v_add_f32_e32 v46, s10, v46
	v_add_f32_e32 v47, s12, v47
	v_add_f32_e32 v46, v46, v47
	v_mul_f32_e32 v47, v100, v39
	v_add_f32_e32 v46, 0x2b8cbccc, v46
	v_rsq_f32_e32 v46, v46
	v_mov_b32_dpp v47, v47 quad_perm:[1,0,3,2] row_mask:0xf bank_mask:0xf bound_ctrl:1
	v_fmac_f32_e32 v47, v100, v39
	v_add_u32_e32 v34, s49, v34
	s_nop 0
	v_add_f32_dpp v39, v47, v47 quad_perm:[2,3,0,1] row_mask:0xf bank_mask:0xf bound_ctrl:1
	s_waitcnt lgkmcnt(4)
	v_mul_f32_e32 v133, v160, v42
	v_mul_f32_e32 v134, v160, v52
	v_add_f32_dpp v39, v39, v39 row_half_mirror row_mask:0xf bank_mask:0xf bound_ctrl:1
	s_nop 1
	v_add_f32_dpp v39, v39, v39 row_mirror row_mask:0xf bank_mask:0xf bound_ctrl:1
	v_fmac_f32_e32 v133, v43, v161
	v_readlane_b32 s31, v39, 0
	v_readlane_b32 s53, v39, 16
	v_readlane_b32 s34, v39, 32
	v_readlane_b32 s54, v39, 48
	v_mul_f32_e64 v39, v41, -v46
	ds_write2st64_b32 v34, v39, v38 offset1:1
	v_mul_f32_e64 v38, v40, -v39
	ds_write2st64_b32 v34, v38, v36 offset0:2 offset1:3
	ds_write2st64_b32 v34, v35, v37 offset0:4 offset1:5
	v_cvt_f32_f16_e32 v36, v106
	v_cvt_f32_f16_e32 v35, v104
	s_waitcnt vmcnt(3)
	v_cvt_f32_ubyte0_e32 v39, v122
	v_mul_f32_e32 v40, 0x3b808081, v39
	v_mul_f32_e32 v41, v102, v36
	v_mul_f32_e32 v46, v41, v41
	v_fma_f32 v39, v39, s45, -1.0
	v_fma_f32 v39, v101, v39, 1.0
	v_mov_b32_dpp v46, v46 quad_perm:[1,0,3,2] row_mask:0xf bank_mask:0xf bound_ctrl:1
	v_fmac_f32_e32 v46, v41, v41
	v_mul_f32_e32 v36, v39, v36
	v_mul_f32_e32 v39, v36, v35
	v_add_f32_dpp v46, v46, v46 quad_perm:[2,3,0,1] row_mask:0xf bank_mask:0xf bound_ctrl:1
	v_cvt_f32_ubyte0_e32 v38, v112
	v_mul_f32_e32 v38, 0xbb1be179, v38
	v_add_f32_dpp v46, v46, v46 row_half_mirror row_mask:0xf bank_mask:0xf bound_ctrl:1
	v_mul_f32_e32 v38, 0x3fb8aa3b, v38
	v_exp_f32_e32 v38, v38
	v_add_f32_dpp v46, v46, v46 row_mirror row_mask:0xf bank_mask:0xf bound_ctrl:1
	v_cvt_f32_f16_e32 v37, v107
	v_readlane_b32 s11, v46, 16
	v_readlane_b32 s13, v46, 48
	v_readlane_b32 s10, v46, 0
	v_readlane_b32 s12, v46, 32
	v_mov_b32_e32 v46, s11
	v_mov_b32_e32 v47, s13
	v_add_f32_e32 v46, s10, v46
	v_add_f32_e32 v47, s12, v47
	v_add_f32_e32 v46, v46, v47
	v_mul_f32_e32 v47, v100, v39
	v_add_f32_e32 v46, 0x2b8cbccc, v46
	v_rsq_f32_e32 v46, v46
	v_mov_b32_dpp v47, v47 quad_perm:[1,0,3,2] row_mask:0xf bank_mask:0xf bound_ctrl:1
	v_fmac_f32_e32 v47, v100, v39
	v_fmac_f32_e32 v134, v53, v161
	v_fmac_f32_e32 v133, v44, v162
	v_add_f32_dpp v39, v47, v47 quad_perm:[2,3,0,1] row_mask:0xf bank_mask:0xf bound_ctrl:1
	v_fmac_f32_e32 v134, v54, v162
	s_nop 0
	v_add_f32_dpp v39, v39, v39 row_half_mirror row_mask:0xf bank_mask:0xf bound_ctrl:1
	v_fmac_f32_e32 v133, v45, v163
	v_fmac_f32_e32 v134, v55, v163
	v_add_f32_dpp v39, v39, v39 row_mirror row_mask:0xf bank_mask:0xf bound_ctrl:1
	s_nop 0
	v_readlane_b32 s55, v39, 0
	v_readlane_b32 s58, v39, 16
	v_readlane_b32 s59, v39, 32
	v_readlane_b32 s61, v39, 48
	v_mul_f32_e64 v39, v41, -v46
	ds_write2st64_b32 v34, v39, v38 offset0:6 offset1:7
	v_mul_f32_e64 v38, v40, -v39
	ds_write2st64_b32 v34, v38, v36 offset0:8 offset1:9
	ds_write2st64_b32 v34, v35, v37 offset0:10 offset1:11
	v_cvt_f32_f16_e32 v36, v108
	s_waitcnt vmcnt(2)
	v_cvt_f32_f16_e32 v35, v110
	s_waitcnt vmcnt(0)
	v_cvt_f32_ubyte0_e32 v39, v120
	v_mul_f32_e32 v40, 0x3b808081, v39
	v_mul_f32_e32 v41, v102, v36
	v_mul_f32_e32 v46, v41, v41
	v_fma_f32 v39, v39, s45, -1.0
	v_fma_f32 v39, v101, v39, 1.0
	v_mov_b32_dpp v46, v46 quad_perm:[1,0,3,2] row_mask:0xf bank_mask:0xf bound_ctrl:1
	v_fmac_f32_e32 v46, v41, v41
	v_mul_f32_e32 v36, v39, v36
	v_mul_f32_e32 v39, v36, v35
	v_add_f32_dpp v46, v46, v46 quad_perm:[2,3,0,1] row_mask:0xf bank_mask:0xf bound_ctrl:1
	v_cvt_f32_ubyte0_e32 v38, v119
	v_mul_f32_e32 v38, 0xbb1be179, v38
	v_add_f32_dpp v46, v46, v46 row_half_mirror row_mask:0xf bank_mask:0xf bound_ctrl:1
	v_mul_f32_e32 v38, 0x3fb8aa3b, v38
	v_exp_f32_e32 v38, v38
	v_add_f32_dpp v46, v46, v46 row_mirror row_mask:0xf bank_mask:0xf bound_ctrl:1
	s_waitcnt lgkmcnt(9)
	v_fmac_f32_e32 v133, v48, v164
	v_readlane_b32 s11, v46, 16
	v_readlane_b32 s13, v46, 48
	v_readlane_b32 s10, v46, 0
	v_readlane_b32 s12, v46, 32
	v_mov_b32_e32 v46, s11
	v_mov_b32_e32 v47, s13
	v_add_f32_e32 v46, s10, v46
	v_add_f32_e32 v47, s12, v47
	v_add_f32_e32 v46, v46, v47
	v_mul_f32_e32 v47, v100, v39
	v_add_f32_e32 v46, 0x2b8cbccc, v46
	v_rsq_f32_e32 v46, v46
	v_mov_b32_dpp v47, v47 quad_perm:[1,0,3,2] row_mask:0xf bank_mask:0xf bound_ctrl:1
	v_fmac_f32_e32 v47, v100, v39
	v_fmac_f32_e32 v134, v56, v164
	v_fmac_f32_e32 v133, v49, v165
	v_add_f32_dpp v39, v47, v47 quad_perm:[2,3,0,1] row_mask:0xf bank_mask:0xf bound_ctrl:1
	v_fmac_f32_e32 v134, v57, v165
	v_cvt_f32_f16_e32 v37, v111
	v_add_f32_dpp v39, v39, v39 row_half_mirror row_mask:0xf bank_mask:0xf bound_ctrl:1
	s_cmpk_lg_i32 s52, 0x5f
	s_cselect_b64 s[10:11], -1, 0
	v_add_f32_dpp v39, v39, v39 row_mirror row_mask:0xf bank_mask:0xf bound_ctrl:1
	v_fmac_f32_e32 v133, v50, v166
	v_fmac_f32_e32 v134, v58, v166
	v_readlane_b32 s68, v39, 0
	v_readlane_b32 s69, v39, 16
	v_readlane_b32 s71, v39, 32
	v_readlane_b32 s72, v39, 48
	v_mul_f32_e64 v39, v41, -v46
	ds_write2st64_b32 v34, v39, v38 offset0:12 offset1:13
	v_fmac_f32_e32 v133, v51, v167
	v_fmac_f32_e32 v134, v59, v167
	v_mul_f32_e64 v38, v40, -v39
	s_and_b64 s[12:13], s[0:1], s[10:11]
	s_nop 1
	v_add_f32_dpp v95, v95, v95 quad_perm:[1,0,3,2] row_mask:0xf bank_mask:0xf bound_ctrl:1
	v_add_f32_dpp v96, v96, v96 quad_perm:[1,0,3,2] row_mask:0xf bank_mask:0xf bound_ctrl:1
	s_nop 0
	v_add_f32_dpp v95, v95, v95 quad_perm:[2,3,0,1] row_mask:0xf bank_mask:0xf bound_ctrl:1
	v_add_f32_dpp v96, v96, v96 quad_perm:[2,3,0,1] row_mask:0xf bank_mask:0xf bound_ctrl:1
	s_nop 0
	v_add_f32_dpp v95, v95, v95 row_half_mirror row_mask:0xf bank_mask:0xf bound_ctrl:1
	v_add_f32_dpp v96, v96, v96 row_half_mirror row_mask:0xf bank_mask:0xf bound_ctrl:1
	s_nop 1
	v_add_f32_dpp v98, v98, v98 quad_perm:[1,0,3,2] row_mask:0xf bank_mask:0xf bound_ctrl:1
	v_add_f32_dpp v99, v99, v99 quad_perm:[1,0,3,2] row_mask:0xf bank_mask:0xf bound_ctrl:1
	s_nop 0
	v_add_f32_dpp v98, v98, v98 quad_perm:[2,3,0,1] row_mask:0xf bank_mask:0xf bound_ctrl:1
	v_add_f32_dpp v99, v99, v99 quad_perm:[2,3,0,1] row_mask:0xf bank_mask:0xf bound_ctrl:1
	s_nop 0
	v_add_f32_dpp v98, v98, v98 row_half_mirror row_mask:0xf bank_mask:0xf bound_ctrl:1
	v_add_f32_dpp v99, v99, v99 row_half_mirror row_mask:0xf bank_mask:0xf bound_ctrl:1
	s_nop 1
	v_add_f32_dpp v103, v103, v103 quad_perm:[1,0,3,2] row_mask:0xf bank_mask:0xf bound_ctrl:1
	v_add_f32_dpp v121, v121, v121 quad_perm:[1,0,3,2] row_mask:0xf bank_mask:0xf bound_ctrl:1
	s_nop 0
	v_add_f32_dpp v103, v103, v103 quad_perm:[2,3,0,1] row_mask:0xf bank_mask:0xf bound_ctrl:1
	v_add_f32_dpp v121, v121, v121 quad_perm:[2,3,0,1] row_mask:0xf bank_mask:0xf bound_ctrl:1
	s_nop 0
	v_add_f32_dpp v103, v103, v103 row_half_mirror row_mask:0xf bank_mask:0xf bound_ctrl:1
	v_add_f32_dpp v121, v121, v121 row_half_mirror row_mask:0xf bank_mask:0xf bound_ctrl:1
	s_nop 1
	v_add_f32_dpp v125, v125, v125 quad_perm:[1,0,3,2] row_mask:0xf bank_mask:0xf bound_ctrl:1
	v_add_f32_dpp v126, v126, v126 quad_perm:[1,0,3,2] row_mask:0xf bank_mask:0xf bound_ctrl:1
	s_nop 0
	v_add_f32_dpp v125, v125, v125 quad_perm:[2,3,0,1] row_mask:0xf bank_mask:0xf bound_ctrl:1
	v_add_f32_dpp v126, v126, v126 quad_perm:[2,3,0,1] row_mask:0xf bank_mask:0xf bound_ctrl:1
	s_nop 0
	v_add_f32_dpp v125, v125, v125 row_half_mirror row_mask:0xf bank_mask:0xf bound_ctrl:1
	v_add_f32_dpp v126, v126, v126 row_half_mirror row_mask:0xf bank_mask:0xf bound_ctrl:1
	s_nop 1
	v_add_f32_dpp v127, v127, v127 quad_perm:[1,0,3,2] row_mask:0xf bank_mask:0xf bound_ctrl:1
	v_add_f32_dpp v128, v128, v128 quad_perm:[1,0,3,2] row_mask:0xf bank_mask:0xf bound_ctrl:1
	s_nop 0
	v_add_f32_dpp v127, v127, v127 quad_perm:[2,3,0,1] row_mask:0xf bank_mask:0xf bound_ctrl:1
	v_add_f32_dpp v128, v128, v128 quad_perm:[2,3,0,1] row_mask:0xf bank_mask:0xf bound_ctrl:1
	s_nop 0
	v_add_f32_dpp v127, v127, v127 row_half_mirror row_mask:0xf bank_mask:0xf bound_ctrl:1
	v_add_f32_dpp v128, v128, v128 row_half_mirror row_mask:0xf bank_mask:0xf bound_ctrl:1
	s_nop 1
	v_add_f32_dpp v129, v129, v129 quad_perm:[1,0,3,2] row_mask:0xf bank_mask:0xf bound_ctrl:1
	v_add_f32_dpp v130, v130, v130 quad_perm:[1,0,3,2] row_mask:0xf bank_mask:0xf bound_ctrl:1
	s_nop 0
	v_add_f32_dpp v129, v129, v129 quad_perm:[2,3,0,1] row_mask:0xf bank_mask:0xf bound_ctrl:1
	v_add_f32_dpp v130, v130, v130 quad_perm:[2,3,0,1] row_mask:0xf bank_mask:0xf bound_ctrl:1
	s_nop 0
	v_add_f32_dpp v129, v129, v129 row_half_mirror row_mask:0xf bank_mask:0xf bound_ctrl:1
	v_add_f32_dpp v130, v130, v130 row_half_mirror row_mask:0xf bank_mask:0xf bound_ctrl:1
	s_nop 1
	v_add_f32_dpp v131, v131, v131 quad_perm:[1,0,3,2] row_mask:0xf bank_mask:0xf bound_ctrl:1
	v_add_f32_dpp v132, v132, v132 quad_perm:[1,0,3,2] row_mask:0xf bank_mask:0xf bound_ctrl:1
	s_nop 0
	v_add_f32_dpp v131, v131, v131 quad_perm:[2,3,0,1] row_mask:0xf bank_mask:0xf bound_ctrl:1
	v_add_f32_dpp v132, v132, v132 quad_perm:[2,3,0,1] row_mask:0xf bank_mask:0xf bound_ctrl:1
	s_nop 0
	v_add_f32_dpp v131, v131, v131 row_half_mirror row_mask:0xf bank_mask:0xf bound_ctrl:1
	v_add_f32_dpp v132, v132, v132 row_half_mirror row_mask:0xf bank_mask:0xf bound_ctrl:1
	s_nop 1
	v_add_f32_dpp v133, v133, v133 quad_perm:[1,0,3,2] row_mask:0xf bank_mask:0xf bound_ctrl:1
	v_add_f32_dpp v134, v134, v134 quad_perm:[1,0,3,2] row_mask:0xf bank_mask:0xf bound_ctrl:1
	s_nop 0
	v_add_f32_dpp v133, v133, v133 quad_perm:[2,3,0,1] row_mask:0xf bank_mask:0xf bound_ctrl:1
	v_add_f32_dpp v134, v134, v134 quad_perm:[2,3,0,1] row_mask:0xf bank_mask:0xf bound_ctrl:1
	s_nop 0
	v_add_f32_dpp v133, v133, v133 row_half_mirror row_mask:0xf bank_mask:0xf bound_ctrl:1
	v_add_f32_dpp v134, v134, v134 row_half_mirror row_mask:0xf bank_mask:0xf bound_ctrl:1
	ds_write2st64_b32 v34, v38, v36 offset0:14 offset1:15
	ds_write2st64_b32 v34, v35, v37 offset0:16 offset1:17
	s_and_saveexec_b64 s[10:11], s[12:13]
	s_cbranch_execz .LBB0_1081
	s_and_b64 vcc, exec, s[8:9]
	s_mov_b64 s[12:13], -1
	s_cbranch_vccnz .LBB0_1072
	v_sub_co_u32_e64 v34, s[12:13], s52, 63
	s_nop 0
	v_readfirstlane_b32 s63, v34
	s_lshr_b32 s63, s63, 4
	s_add_i32 s63, s63, 1
	s_and_b32 s73, s91, 15
	s_and_b64 s[12:13], s[12:13], exec
	s_cselect_b32 s70, 0, s63
	s_cselect_b32 s63, s91, s73
	s_mov_b64 s[12:13], 0

.LBB0_1124:
	s_add_i32 s11, s12, s83
	s_add_i32 s14, s12, s2
	s_cmp_lg_u32 s12, 0
	s_cselect_b64 s[8:9], -1, 0
	s_and_b64 s[12:13], s[8:9], exec
	s_cselect_b32 s14, s14, s82
	s_or_b64 s[8:9], s[20:21], s[8:9]
	s_and_b64 s[12:13], s[20:21], exec
	s_cselect_b32 s11, s11, s14
	s_and_b64 s[12:13], s[8:9], exec
	s_cselect_b32 s12, s84, 0x400
	s_lshl_b32 s10, s10, 4
	s_or_b32 s10, s10, s95
	s_xor_b32 s17, s10, -4
	s_and_b32 s13, s11, 1
	s_or_b32 s14, s10, 2
	s_xor_b32 s15, s10, -3
	s_or_b32 s16, s10, 3
	s_add_i32 s17, s17, s12
	s_cmp_eq_u32 s13, 0
	s_cselect_b32 s16, s16, s17
	s_add_i32 s15, s15, s12
	s_cmp_eq_u32 s13, 0
	s_cselect_b32 s14, s14, s15
	s_xor_b32 s17, s10, -2
	s_or_b32 s15, s10, 1
	s_add_i32 s17, s17, s12
	s_cmp_eq_u32 s13, 0
	s_cselect_b32 s15, s15, s17
	s_not_b32 s17, s10
	s_add_i32 s12, s12, s17
	s_cmp_eq_u32 s13, 0
	s_cselect_b32 s10, s10, s12
	s_ashr_i32 s12, s11, 6
	s_lshl_b32 s17, s12, 10
	s_addk_i32 s17, 0x2000
	s_lshl_b32 s12, s12, 8
	s_and_b64 s[8:9], s[8:9], exec
	v_lshrrev_b32_e32 v2, s36, v168
	s_cselect_b32 s12, s12, s17
	s_lshl_b32 s8, s11, 5
	v_mul_lo_u32 v2, s60, v2
	s_and_b32 s8, s8, 0x7c0
	v_bfe_u32 v3, v168, 0, s36
	v_lshlrev_b32_e32 v2, 5, v2
	v_or_b32_e32 v8, s8, v168
	v_readlane_b32 s64, v237, 2
	v_lshl_add_u32 v70, v3, 4, v2
	v_lshlrev_b32_e32 v2, 2, v8
	v_readlane_b32 s65, v237, 3
	s_lshl_b32 s34, s8, 1
	v_readlane_b32 s66, v237, 4
	v_readlane_b32 s67, v237, 5
	v_readlane_b32 s68, v237, 6
	v_readlane_b32 s69, v237, 7
	global_load_dword v102, v2, s[64:65]
	s_nop 1
	global_load_dword v101, v2, s[66:67]
	s_nop 0
	global_load_dword v100, v2, s[68:69]
	v_lshl_add_u64 v[2:3], v[76:77], 0, s[34:35]
	s_add_i32 s10, s12, s10
	s_mulk_i32 s13, 0x3000
	s_ashr_i32 s11, s10, 31
	ds_read_b128 v[138:141], v83 offset:12288
	ds_read_b128 v[26:29], v83 offset:12304
	v_mad_i64_i32 v[4:5], s[8:9], s10, v73, v[2:3]
	s_add_u32 s8, s10, s13
	global_load_ushort v109, v[4:5], off
	v_add_co_u32_e32 v4, vcc, s43, v4
	ds_read_b128 v[10:13], v83 offset:12544
	ds_read_b128 v[14:17], v83 offset:12560
	s_addc_u32 s9, s11, 0
	s_nop 0
	v_addc_co_u32_e32 v5, vcc, 0, v5, vcc
	s_lshl_b64 s[8:9], s[8:9], 11
	ds_read_b128 v[18:21], v83 offset:12800
	ds_read_b128 v[22:25], v83 offset:12816
	global_load_ushort v123, v[4:5], off offset:-4096
	global_load_ushort v124, v[4:5], off
	v_mov_b32_e32 v5, s9
	v_or_b32_e32 v4, s8, v8
	v_lshl_add_u64 v[6:7], s[22:23], 0, v[4:5]
	v_lshl_add_u64 v[4:5], s[24:25], 0, v[4:5]
	s_add_i32 s10, s12, s15
	global_load_ubyte v115, v[6:7], off
	global_load_ubyte v116, v[4:5], off
	s_ashr_i32 s11, s10, 31
	v_mad_i64_i32 v[4:5], s[8:9], s10, v73, v[2:3]
	s_add_u32 s8, s10, s13
	global_load_ushort v105, v[4:5], off
	v_add_co_u32_e32 v4, vcc, s43, v4
	s_addc_u32 s9, s11, 0
	s_nop 0
	v_addc_co_u32_e32 v5, vcc, 0, v5, vcc
	s_lshl_b64 s[8:9], s[8:9], 11
	global_load_ushort v117, v[4:5], off offset:-4096
	global_load_ushort v118, v[4:5], off
	v_mov_b32_e32 v5, s9
	ds_read_b128 v[142:145], v83 offset:13056
	ds_read_b128 v[30:33], v83 offset:13072
	v_or_b32_e32 v4, s8, v8
	v_lshl_add_u64 v[6:7], s[22:23], 0, v[4:5]
	v_lshl_add_u64 v[4:5], s[24:25], 0, v[4:5]
	s_add_i32 s10, s12, s14
	global_load_ubyte v113, v[6:7], off
	ds_read_b128 v[34:37], v83 offset:13312
	ds_read_b128 v[38:41], v83 offset:13328
	global_load_ubyte v114, v[4:5], off
	s_ashr_i32 s11, s10, 31
	v_mad_i64_i32 v[4:5], s[8:9], s10, v73, v[2:3]
	s_add_u32 s8, s10, s13
	global_load_ushort v104, v[4:5], off
	v_add_co_u32_e32 v4, vcc, s43, v4
	ds_read_b64 v[136:137], v82 offset:13568
	s_addc_u32 s9, s11, 0
	s_nop 0
	v_addc_co_u32_e32 v5, vcc, 0, v5, vcc
	s_lshl_b64 s[8:9], s[8:9], 11
	s_add_i32 s12, s12, s16
	global_load_ushort v106, v[4:5], off offset:-4096
	global_load_ushort v107, v[4:5], off
	v_mov_b32_e32 v5, s9
	v_or_b32_e32 v4, s8, v8
	s_ashr_i32 s10, s12, 31
	v_mad_i64_i32 v[2:3], s[8:9], s12, v73, v[2:3]
	v_lshl_add_u64 v[6:7], s[22:23], 0, v[4:5]
	v_lshl_add_u64 v[4:5], s[24:25], 0, v[4:5]
	s_add_u32 s8, s12, s13
	global_load_ubyte v112, v[6:7], off
	global_load_ubyte v122, v[4:5], off
	global_load_ushort v110, v[2:3], off
	v_add_co_u32_e32 v2, vcc, s43, v2
	s_addc_u32 s9, s10, 0
	s_nop 0
	v_addc_co_u32_e32 v3, vcc, 0, v3, vcc
	s_lshl_b64 s[8:9], s[8:9], 11
	global_load_ushort v108, v[2:3], off offset:-4096
	global_load_ushort v111, v[2:3], off
	v_mov_b32_e32 v3, s9
	v_or_b32_e32 v2, s8, v8
	v_lshl_add_u64 v[4:5], s[22:23], 0, v[2:3]
	v_lshl_add_u64 v[2:3], s[24:25], 0, v[2:3]
	global_load_ubyte v119, v[4:5], off
	global_load_ubyte v120, v[2:3], off
	s_nop 0
	s_waitcnt lgkmcnt(10)
	v_mul_f32_e32 v65, v42, v138
	v_mul_f32_e32 v138, v52, v138
	v_fmac_f32_e32 v65, v43, v139
	v_fmac_f32_e32 v138, v53, v139
	v_fmac_f32_e32 v65, v44, v140
	v_fmac_f32_e32 v138, v54, v140
	v_fmac_f32_e32 v65, v45, v141
	v_fmac_f32_e32 v138, v55, v141
	s_waitcnt lgkmcnt(9)
	v_fmac_f32_e32 v65, v48, v26
	v_fmac_f32_e32 v138, v56, v26
	v_fmac_f32_e32 v65, v49, v27
	v_fmac_f32_e32 v138, v57, v27
	v_fmac_f32_e32 v65, v50, v28
	v_fmac_f32_e32 v138, v58, v28
	v_fmac_f32_e32 v65, v51, v29
	v_fmac_f32_e32 v138, v59, v29
	s_nop 1
	v_add_f32_dpp v65, v65, v65 quad_perm:[1,0,3,2] row_mask:0xf bank_mask:0xf bound_ctrl:1
	v_add_f32_dpp v138, v138, v138 quad_perm:[1,0,3,2] row_mask:0xf bank_mask:0xf bound_ctrl:1
	s_nop 0
	v_add_f32_dpp v65, v65, v65 quad_perm:[2,3,0,1] row_mask:0xf bank_mask:0xf bound_ctrl:1
	v_add_f32_dpp v138, v138, v138 quad_perm:[2,3,0,1] row_mask:0xf bank_mask:0xf bound_ctrl:1
	s_nop 0
	v_add_f32_dpp v65, v65, v65 row_half_mirror row_mask:0xf bank_mask:0xf bound_ctrl:1
	ds_read_b128 v[146:149], v83 offset:13824
	ds_read_b128 v[26:29], v83 offset:13840
	v_add_f32_dpp v138, v138, v138 row_half_mirror row_mask:0xf bank_mask:0xf bound_ctrl:1
	s_waitcnt lgkmcnt(7)
	v_mul_f32_e32 v64, v22, v65
	v_fmac_f32_e32 v64, v48, v14
	v_mul_f32_e32 v48, v23, v65
	v_fmac_f32_e32 v48, v49, v15
	ds_read_b128 v[150:153], v83 offset:14080
	ds_read_b128 v[6:9], v83 offset:14096
	v_mul_f32_e32 v49, v24, v65
	v_fmac_f32_e32 v49, v50, v16
	v_mul_f32_e32 v50, v25, v65
	s_nop 0
	v_fmac_f32_e32 v50, v51, v17
	v_mul_f32_e32 v60, v18, v65
	ds_read_b128 v[154:157], v83 offset:14336
	ds_read_b128 v[158:161], v83 offset:14352
	v_mul_f32_e32 v51, v18, v138
	v_fmac_f32_e32 v60, v42, v10
	v_mul_f32_e32 v61, v19, v65
	v_mul_f32_e32 v62, v20, v65
	v_mul_f32_e32 v63, v21, v65
	v_fmac_f32_e32 v51, v52, v10
	v_mul_f32_e32 v65, v19, v138
	v_fmac_f32_e32 v61, v43, v11
	s_waitcnt lgkmcnt(6)
	v_fmac_f32_e32 v60, v136, v142
	v_fmac_f32_e32 v62, v44, v12
	v_fmac_f32_e32 v63, v45, v13
	v_fmac_f32_e32 v51, v137, v142
	v_fmac_f32_e32 v65, v53, v11
	v_mul_f32_e32 v66, v20, v138
	s_nop 0
	v_fmac_f32_e32 v61, v136, v143
	v_fmac_f32_e32 v62, v136, v144
	v_fmac_f32_e32 v63, v136, v145
	v_fmac_f32_e32 v64, v136, v30
	v_fmac_f32_e32 v48, v136, v31
	v_fmac_f32_e32 v49, v136, v32
	v_fmac_f32_e32 v50, v136, v33
	v_mul_f32_e32 v135, v34, v60
	v_fmac_f32_e32 v65, v137, v143
	v_fmac_f32_e32 v66, v54, v12
	v_mul_f32_e32 v67, v21, v138
	v_mul_f32_e32 v136, v34, v51
	v_fmac_f32_e32 v66, v137, v144
	v_fmac_f32_e32 v135, v61, v35
	v_fmac_f32_e32 v67, v55, v13
	v_mul_f32_e32 v68, v22, v138
	v_fmac_f32_e32 v136, v65, v35
	v_fmac_f32_e32 v67, v137, v145
	v_fmac_f32_e32 v135, v62, v36
	v_fmac_f32_e32 v68, v56, v14
	v_mul_f32_e32 v69, v23, v138
	v_fmac_f32_e32 v136, v66, v36
	ds_read_b128 v[10:13], v83 offset:14592
	ds_read_b128 v[18:21], v83 offset:14608
	ds_read_b128 v[162:165], v83 offset:14848
	ds_read_b128 v[178:181], v83 offset:14864
	v_fmac_f32_e32 v68, v137, v30
	v_fmac_f32_e32 v135, v63, v37
	v_fmac_f32_e32 v69, v57, v15
	v_mul_f32_e32 v80, v24, v138
	v_fmac_f32_e32 v136, v67, v37
	v_fmac_f32_e32 v69, v137, v31
	v_fmac_f32_e32 v135, v64, v38
	v_fmac_f32_e32 v80, v58, v16
	v_mul_f32_e32 v81, v25, v138
	ds_read_b64 v[138:139], v82 offset:15104
	v_fmac_f32_e32 v136, v68, v38
	v_fmac_f32_e32 v80, v137, v32
	v_fmac_f32_e32 v135, v48, v39
	v_fmac_f32_e32 v81, v59, v17
	ds_read_b128 v[188:191], v83 offset:15360
	ds_read_b128 v[42:45], v83 offset:15376
	v_fmac_f32_e32 v136, v69, v39
	v_fmac_f32_e32 v81, v137, v33
	v_fmac_f32_e32 v135, v49, v40
	v_fmac_f32_e32 v136, v80, v40
	global_load_dwordx4 v[2:5], v70, s[38:39]
	v_fmac_f32_e32 v135, v50, v41
	v_fmac_f32_e32 v136, v81, v41
	s_nop 0
	s_waitcnt lgkmcnt(12)
	v_mul_f32_e32 v59, v60, v146
	v_mul_f32_e32 v146, v51, v146
	v_fmac_f32_e32 v59, v61, v147
	v_fmac_f32_e32 v146, v65, v147
	v_fmac_f32_e32 v59, v62, v148
	v_fmac_f32_e32 v146, v66, v148
	v_fmac_f32_e32 v59, v63, v149
	v_fmac_f32_e32 v146, v67, v149
	s_waitcnt lgkmcnt(11)
	v_fmac_f32_e32 v59, v64, v26
	v_fmac_f32_e32 v146, v68, v26
	s_mov_b32 s61, s35
	v_fmac_f32_e32 v59, v48, v27
	v_fmac_f32_e32 v146, v69, v27
	v_fmac_f32_e32 v59, v49, v28
	v_fmac_f32_e32 v146, v80, v28
	v_fmac_f32_e32 v59, v50, v29
	v_fmac_f32_e32 v146, v81, v29
	s_nop 1
	v_add_f32_dpp v59, v59, v59 quad_perm:[1,0,3,2] row_mask:0xf bank_mask:0xf bound_ctrl:1
	v_add_f32_dpp v146, v146, v146 quad_perm:[1,0,3,2] row_mask:0xf bank_mask:0xf bound_ctrl:1
	s_nop 0
	v_add_f32_dpp v59, v59, v59 quad_perm:[2,3,0,1] row_mask:0xf bank_mask:0xf bound_ctrl:1
	v_add_f32_dpp v146, v146, v146 quad_perm:[2,3,0,1] row_mask:0xf bank_mask:0xf bound_ctrl:1
	ds_read_b128 v[194:197], v83 offset:15616
	ds_read_b128 v[202:205], v83 offset:15632
	ds_read_b128 v[34:37], v83 offset:15872
	ds_read_b128 v[14:17], v83 offset:15888
	s_nop 0
	v_add_f32_dpp v59, v59, v59 row_half_mirror row_mask:0xf bank_mask:0xf bound_ctrl:1
	v_add_f32_dpp v146, v146, v146 row_half_mirror row_mask:0xf bank_mask:0xf bound_ctrl:1
	v_lshl_add_u64 v[46:47], s[38:39], 0, v[70:71]
	s_waitcnt lgkmcnt(12)
	v_mul_f32_e32 v52, v154, v59
	v_fmac_f32_e32 v52, v60, v150
	v_mul_f32_e32 v53, v155, v59
	v_mul_f32_e32 v54, v156, v59
	v_mul_f32_e32 v55, v157, v59
	s_waitcnt lgkmcnt(11)
	v_mul_f32_e32 v56, v158, v59
	v_mul_f32_e32 v57, v159, v59
	v_mul_f32_e32 v58, v160, v59
	v_mul_f32_e32 v59, v161, v59
	v_mul_f32_e32 v60, v154, v146
	s_lshl_b64 s[8:9], s[60:61], 2
	v_fmac_f32_e32 v60, v51, v150
	v_fmac_f32_e32 v59, v50, v9
	v_mul_f32_e32 v142, v158, v146
	v_mul_f32_e32 v143, v159, v146
	v_mul_f32_e32 v144, v160, v146
	v_mul_f32_e32 v145, v161, v146
	v_lshl_add_u64 v[50:51], v[46:47], 0, s[8:9]
	v_fmac_f32_e32 v53, v61, v151
	v_fmac_f32_e32 v54, v62, v152
	v_fmac_f32_e32 v56, v64, v6
	v_fmac_f32_e32 v57, v48, v7
	v_fmac_f32_e32 v58, v49, v8
	v_mul_f32_e32 v61, v155, v146
	v_mul_f32_e32 v62, v156, v146
	v_mul_f32_e32 v140, v157, v146
	v_fmac_f32_e32 v142, v68, v6
	v_fmac_f32_e32 v143, v69, v7
	v_fmac_f32_e32 v144, v80, v8
	v_fmac_f32_e32 v145, v81, v9
	global_load_dwordx4 v[6:9], v[50:51], off
	v_fmac_f32_e32 v61, v65, v151
	s_waitcnt lgkmcnt(6)
	v_fmac_f32_e32 v52, v138, v10
	v_fmac_f32_e32 v60, v139, v10
	ds_read_b128 v[38:41], v83 offset:16128
	ds_read_b128 v[22:25], v83 offset:16144
	v_fmac_f32_e32 v62, v66, v152
	v_fmac_f32_e32 v53, v138, v11
	v_fmac_f32_e32 v55, v63, v153
	v_fmac_f32_e32 v61, v139, v11
	s_waitcnt lgkmcnt(7)
	v_mul_f32_e32 v63, v52, v188
	v_mul_f32_e32 v188, v60, v188
	v_fmac_f32_e32 v140, v67, v153
	v_fmac_f32_e32 v54, v138, v12
	v_fmac_f32_e32 v62, v139, v12
	s_nop 0
	v_fmac_f32_e32 v63, v53, v189
	v_fmac_f32_e32 v188, v61, v189
	v_fmac_f32_e32 v55, v138, v13
	v_fmac_f32_e32 v56, v138, v18
	v_fmac_f32_e32 v57, v138, v19
	ds_read_b128 v[30:33], v83 offset:16384
	ds_read_b128 v[26:29], v83 offset:16400
	ds_read_b64 v[146:147], v82 offset:16640
	v_fmac_f32_e32 v58, v138, v20
	v_fmac_f32_e32 v59, v138, v21
	v_mul_f32_e32 v137, v162, v52
	v_fmac_f32_e32 v140, v139, v13
	v_mul_f32_e32 v138, v162, v60
	v_fmac_f32_e32 v142, v139, v18
	v_fmac_f32_e32 v63, v54, v190
	v_fmac_f32_e32 v188, v62, v190
	v_fmac_f32_e32 v137, v53, v163
	v_fmac_f32_e32 v143, v139, v19
	v_fmac_f32_e32 v144, v139, v20
	ds_read_b128 v[154:157], v83 offset:16896
	ds_read_b128 v[46:49], v83 offset:16912
	v_fmac_f32_e32 v145, v139, v21
	v_fmac_f32_e32 v138, v61, v163
	v_fmac_f32_e32 v63, v55, v191
	v_fmac_f32_e32 v188, v140, v191
	v_fmac_f32_e32 v137, v54, v164
	v_fmac_f32_e32 v138, v62, v164
	s_waitcnt lgkmcnt(11)
	v_fmac_f32_e32 v63, v56, v42
	v_fmac_f32_e32 v188, v142, v42
	v_fmac_f32_e32 v137, v55, v165
	v_fmac_f32_e32 v138, v140, v165
	s_nop 0
	v_fmac_f32_e32 v63, v57, v43
	v_fmac_f32_e32 v188, v143, v43
	v_fmac_f32_e32 v137, v56, v178
	v_fmac_f32_e32 v138, v142, v178
	v_fmac_f32_e32 v63, v58, v44
	v_fmac_f32_e32 v188, v144, v44
	v_fmac_f32_e32 v137, v57, v179
	v_fmac_f32_e32 v138, v143, v179
	v_fmac_f32_e32 v63, v59, v45
	v_fmac_f32_e32 v188, v145, v45
	v_fmac_f32_e32 v137, v58, v180
	v_fmac_f32_e32 v138, v144, v180
	s_nop 1
	v_add_f32_dpp v63, v63, v63 quad_perm:[1,0,3,2] row_mask:0xf bank_mask:0xf bound_ctrl:1
	v_add_f32_dpp v188, v188, v188 quad_perm:[1,0,3,2] row_mask:0xf bank_mask:0xf bound_ctrl:1
	s_nop 0
	v_add_f32_dpp v63, v63, v63 quad_perm:[2,3,0,1] row_mask:0xf bank_mask:0xf bound_ctrl:1
	v_add_f32_dpp v188, v188, v188 quad_perm:[2,3,0,1] row_mask:0xf bank_mask:0xf bound_ctrl:1
	s_nop 0
	v_add_f32_dpp v63, v63, v63 row_half_mirror row_mask:0xf bank_mask:0xf bound_ctrl:1
	v_add_f32_dpp v188, v188, v188 row_half_mirror row_mask:0xf bank_mask:0xf bound_ctrl:1
	v_fmac_f32_e32 v137, v59, v181
	s_waitcnt lgkmcnt(8)
	v_mul_f32_e32 v80, v36, v63
	v_mul_f32_e32 v70, v37, v63
	s_waitcnt lgkmcnt(7)
	v_mul_f32_e32 v67, v16, v63
	v_mul_f32_e32 v66, v17, v63
	v_mul_f32_e32 v65, v34, v188
	v_mul_f32_e32 v64, v35, v188
	v_fmac_f32_e32 v138, v145, v181
	v_mul_f32_e32 v141, v34, v63
	ds_read_b128 v[158:161], v83 offset:17152
	ds_read_b128 v[162:165], v83 offset:17168
	ds_read_b128 v[178:181], v83 offset:17408
	ds_read_b128 v[206:209], v83 offset:17424
	v_mul_f32_e32 v81, v35, v63
	v_fmac_f32_e32 v80, v54, v196
	v_fmac_f32_e32 v70, v55, v197
	v_mul_f32_e32 v69, v14, v63
	v_mul_f32_e32 v68, v15, v63
	v_fmac_f32_e32 v67, v58, v204
	v_fmac_f32_e32 v66, v59, v205
	v_fmac_f32_e32 v65, v60, v194
	v_fmac_f32_e32 v64, v61, v195
	ds_read_b128 v[42:45], v83 offset:17664
	ds_read_b128 v[212:215], v83 offset:17680
	v_mul_f32_e32 v63, v36, v188
	v_mul_f32_e32 v61, v14, v188
	ds_read_b128 v[220:223], v83 offset:17920
	ds_read_b128 v[18:21], v83 offset:17936
	v_mul_f32_e32 v60, v15, v188
	v_mul_f32_e32 v59, v16, v188
	v_mul_f32_e32 v58, v17, v188
	v_lshl_add_u64 v[54:55], v[50:51], 0, s[8:9]
	v_fmac_f32_e32 v141, v52, v194
	v_fmac_f32_e32 v81, v53, v195
	v_fmac_f32_e32 v69, v56, v202
	v_fmac_f32_e32 v68, v57, v203
	v_fmac_f32_e32 v63, v62, v196
	v_mul_f32_e32 v62, v37, v188
	v_fmac_f32_e32 v61, v142, v202
	v_fmac_f32_e32 v60, v143, v203
	ds_read_b64 v[56:57], v82 offset:18176
	v_fmac_f32_e32 v59, v144, v204
	v_fmac_f32_e32 v58, v145, v205
	global_load_dwordx4 v[10:13], v[54:55], off
	v_fmac_f32_e32 v62, v140, v197
	s_waitcnt lgkmcnt(11)
	v_fmac_f32_e32 v141, v146, v38
	v_fmac_f32_e32 v65, v147, v38
	v_fmac_f32_e32 v81, v146, v39
	v_mul_f32_e32 v139, v30, v141
	v_fmac_f32_e32 v64, v147, v39
	v_mul_f32_e32 v140, v30, v65
	s_nop 0
	s_waitcnt lgkmcnt(10)
	v_mul_f32_e32 v142, v141, v154
	v_fmac_f32_e32 v80, v146, v40
	v_fmac_f32_e32 v139, v81, v31
	v_fmac_f32_e32 v63, v147, v40
	v_fmac_f32_e32 v140, v64, v31
	v_mul_f32_e32 v154, v65, v154
	v_fmac_f32_e32 v70, v146, v41
	v_fmac_f32_e32 v139, v80, v32
	v_fmac_f32_e32 v62, v147, v41
	v_fmac_f32_e32 v140, v63, v32
	s_nop 0
	v_fmac_f32_e32 v142, v81, v155
	v_fmac_f32_e32 v154, v64, v155
	v_fmac_f32_e32 v69, v146, v22
	v_fmac_f32_e32 v139, v70, v33
	v_fmac_f32_e32 v61, v147, v22
	v_fmac_f32_e32 v140, v62, v33
	v_fmac_f32_e32 v142, v80, v156
	v_fmac_f32_e32 v154, v63, v156
	s_nop 0
	v_fmac_f32_e32 v68, v146, v23
	v_fmac_f32_e32 v139, v69, v26
	v_fmac_f32_e32 v60, v147, v23
	v_fmac_f32_e32 v140, v61, v26
	v_fmac_f32_e32 v67, v146, v24
	v_fmac_f32_e32 v142, v70, v157
	v_fmac_f32_e32 v154, v62, v157
	v_fmac_f32_e32 v66, v146, v25
	v_fmac_f32_e32 v139, v68, v27
	v_fmac_f32_e32 v59, v147, v24
	v_fmac_f32_e32 v58, v147, v25
	v_fmac_f32_e32 v140, v60, v27
	s_waitcnt lgkmcnt(9)
	v_fmac_f32_e32 v142, v69, v46
	v_fmac_f32_e32 v154, v61, v46
	s_nop 0
	v_fmac_f32_e32 v139, v67, v28
	v_fmac_f32_e32 v140, v59, v28
	v_fmac_f32_e32 v142, v68, v47
	v_fmac_f32_e32 v154, v60, v47
	v_fmac_f32_e32 v139, v66, v29
	v_fmac_f32_e32 v140, v58, v29
	v_fmac_f32_e32 v142, v67, v48
	v_fmac_f32_e32 v154, v59, v48
	v_fmac_f32_e32 v142, v66, v49
	v_fmac_f32_e32 v154, v58, v49
	s_nop 1
	v_add_f32_dpp v142, v142, v142 quad_perm:[1,0,3,2] row_mask:0xf bank_mask:0xf bound_ctrl:1
	v_add_f32_dpp v154, v154, v154 quad_perm:[1,0,3,2] row_mask:0xf bank_mask:0xf bound_ctrl:1
	s_nop 0
	v_add_f32_dpp v142, v142, v142 quad_perm:[2,3,0,1] row_mask:0xf bank_mask:0xf bound_ctrl:1
	v_add_f32_dpp v154, v154, v154 quad_perm:[2,3,0,1] row_mask:0xf bank_mask:0xf bound_ctrl:1
	s_nop 0
	v_add_f32_dpp v142, v142, v142 row_half_mirror row_mask:0xf bank_mask:0xf bound_ctrl:1
	v_add_f32_dpp v154, v154, v154 row_half_mirror row_mask:0xf bank_mask:0xf bound_ctrl:1
	ds_read_b128 v[188:191], v83 offset:18432
	ds_read_b128 v[24:27], v83 offset:18448
	s_waitcnt lgkmcnt(8)
	v_mul_f32_e32 v143, v178, v142
	v_mul_f32_e32 v144, v179, v142
	v_mul_f32_e32 v148, v178, v154
	v_fmac_f32_e32 v143, v141, v158
	ds_read_b128 v[28:31], v83 offset:18688
	ds_read_b128 v[32:35], v83 offset:18704
	v_fmac_f32_e32 v144, v81, v159
	v_mul_f32_e32 v81, v180, v142
	v_fmac_f32_e32 v148, v65, v158
	v_mul_f32_e32 v149, v179, v154
	ds_read_b128 v[36:39], v83 offset:18944
	ds_read_b128 v[194:197], v83 offset:18960
	v_fmac_f32_e32 v149, v64, v159
	ds_read_b128 v[156:159], v83 offset:19200
	ds_read_b128 v[48:51], v83 offset:19216
	s_waitcnt lgkmcnt(8)
	v_fmac_f32_e32 v143, v56, v42
	v_fmac_f32_e32 v81, v80, v160
	v_mul_f32_e32 v80, v181, v142
	v_fmac_f32_e32 v148, v57, v42
	v_mul_f32_e32 v150, v180, v154
	s_nop 0
	v_fmac_f32_e32 v80, v70, v161
	v_fmac_f32_e32 v144, v56, v43
	v_mul_f32_e32 v70, v206, v142
	v_mul_f32_e32 v145, v207, v142
	ds_read_b128 v[202:205], v83 offset:19456
	v_mul_f32_e32 v146, v208, v142
	ds_read_b128 v[224:227], v83 offset:19472
	v_mul_f32_e32 v147, v209, v142
	v_mul_f32_e32 v141, v220, v143
	v_fmac_f32_e32 v149, v57, v43
	v_fmac_f32_e32 v150, v63, v160
	v_mul_f32_e32 v63, v181, v154
	v_mul_f32_e32 v142, v220, v148
	v_fmac_f32_e32 v63, v62, v161
	v_fmac_f32_e32 v81, v56, v44
	v_fmac_f32_e32 v141, v144, v221
	v_fmac_f32_e32 v150, v57, v44
	v_mul_f32_e32 v62, v206, v154
	v_fmac_f32_e32 v142, v149, v221
	v_mul_f32_e32 v151, v207, v154
	v_fmac_f32_e32 v80, v56, v45
	v_fmac_f32_e32 v70, v69, v162
	v_fmac_f32_e32 v141, v81, v222
	v_fmac_f32_e32 v63, v57, v45
	v_fmac_f32_e32 v62, v61, v162
	v_fmac_f32_e32 v142, v150, v222
	ds_read_b64 v[22:23], v82 offset:19712
	v_mul_f32_e32 v152, v208, v154
	v_fmac_f32_e32 v70, v56, v212
	v_fmac_f32_e32 v145, v68, v163
	v_fmac_f32_e32 v141, v80, v223
	v_fmac_f32_e32 v62, v57, v212
	v_fmac_f32_e32 v151, v60, v163
	v_fmac_f32_e32 v142, v63, v223
	v_mul_f32_e32 v153, v209, v154
	v_fmac_f32_e32 v145, v56, v213
	v_fmac_f32_e32 v146, v67, v164
	v_fmac_f32_e32 v141, v70, v18
	v_fmac_f32_e32 v151, v57, v213
	v_fmac_f32_e32 v152, v59, v164
	v_fmac_f32_e32 v142, v62, v18
	s_nop 0
	v_fmac_f32_e32 v147, v66, v165
	v_fmac_f32_e32 v146, v56, v214
	v_fmac_f32_e32 v141, v145, v19
	v_fmac_f32_e32 v152, v57, v214
	v_fmac_f32_e32 v153, v58, v165
	v_fmac_f32_e32 v142, v151, v19
	v_fmac_f32_e32 v147, v56, v215
	v_fmac_f32_e32 v141, v146, v20
	v_fmac_f32_e32 v153, v57, v215
	v_fmac_f32_e32 v142, v152, v20
	v_lshl_add_u64 v[18:19], v[54:55], 0, s[8:9]
	global_load_dwordx4 v[14:17], v[18:19], off
	v_fmac_f32_e32 v141, v147, v21
	v_fmac_f32_e32 v142, v153, v21
	s_nop 0
	s_waitcnt lgkmcnt(10)
	v_mul_f32_e32 v154, v143, v188
	v_mul_f32_e32 v188, v148, v188
	v_fmac_f32_e32 v154, v144, v189
	v_fmac_f32_e32 v188, v149, v189
	v_fmac_f32_e32 v154, v81, v190
	v_fmac_f32_e32 v188, v150, v190
	v_fmac_f32_e32 v154, v80, v191
	v_fmac_f32_e32 v188, v63, v191
	s_waitcnt lgkmcnt(9)
	v_fmac_f32_e32 v154, v70, v24
	v_fmac_f32_e32 v188, v62, v24
	v_fmac_f32_e32 v154, v145, v25
	v_fmac_f32_e32 v188, v151, v25
	v_fmac_f32_e32 v154, v146, v26
	v_fmac_f32_e32 v188, v152, v26
	v_fmac_f32_e32 v154, v147, v27
	v_fmac_f32_e32 v188, v153, v27
	s_nop 1
	s_nop 1
	s_nop 1
	v_add_f32_dpp v154, v154, v154 quad_perm:[1,0,3,2] row_mask:0xf bank_mask:0xf bound_ctrl:1
	v_add_f32_dpp v188, v188, v188 quad_perm:[1,0,3,2] row_mask:0xf bank_mask:0xf bound_ctrl:1
	s_nop 0
	v_add_f32_dpp v154, v154, v154 quad_perm:[2,3,0,1] row_mask:0xf bank_mask:0xf bound_ctrl:1
	v_add_f32_dpp v188, v188, v188 quad_perm:[2,3,0,1] row_mask:0xf bank_mask:0xf bound_ctrl:1
	s_nop 0
	v_add_f32_dpp v154, v154, v154 row_half_mirror row_mask:0xf bank_mask:0xf bound_ctrl:1
	v_add_f32_dpp v188, v188, v188 row_half_mirror row_mask:0xf bank_mask:0xf bound_ctrl:1
	ds_read_b128 v[58:61], v83 offset:19968
	ds_read_b128 v[54:57], v83 offset:19984
	s_nop 0
	s_waitcnt lgkmcnt(8)
	v_mul_f32_e32 v66, v38, v154
	s_waitcnt lgkmcnt(7)
	v_mul_f32_e32 v68, v194, v154
	v_mul_f32_e32 v64, v36, v154
	ds_read_b128 v[178:181], v83 offset:20224
	ds_read_b128 v[206:209], v83 offset:20240
	v_fmac_f32_e32 v66, v81, v30
	v_mul_f32_e32 v67, v39, v154
	v_fmac_f32_e32 v68, v70, v32
	v_mul_f32_e32 v70, v196, v154
	ds_read_b128 v[212:215], v83 offset:20480
	ds_read_b128 v[220:223], v83 offset:20496
	v_mul_f32_e32 v81, v36, v188
	v_fmac_f32_e32 v64, v143, v28
	v_mul_f32_e32 v65, v37, v154
	ds_read_b128 v[228:231], v83 offset:20736
	ds_read_b128 v[238:241], v83 offset:20752
	v_fmac_f32_e32 v67, v80, v31
	v_fmac_f32_e32 v70, v146, v34
	v_mul_f32_e32 v80, v197, v154
	v_fmac_f32_e32 v81, v148, v28
	v_mul_f32_e32 v146, v37, v188
	v_fmac_f32_e32 v65, v144, v29
	s_waitcnt lgkmcnt(8)
	v_fmac_f32_e32 v64, v22, v156
	v_fmac_f32_e32 v80, v147, v35
	v_fmac_f32_e32 v81, v23, v156
	v_fmac_f32_e32 v146, v149, v29
	v_mul_f32_e32 v147, v38, v188
	v_fmac_f32_e32 v65, v22, v157
	v_mul_f32_e32 v143, v202, v64
	v_fmac_f32_e32 v146, v23, v157
	v_fmac_f32_e32 v147, v150, v30
	v_mul_f32_e32 v148, v39, v188
	v_mul_f32_e32 v144, v202, v81
	v_fmac_f32_e32 v148, v63, v31
	v_fmac_f32_e32 v66, v22, v158
	v_fmac_f32_e32 v143, v65, v203
	ds_read_b128 v[42:45], v83 offset:20992
	ds_read_b128 v[38:41], v83 offset:21008
	ds_read_b64 v[160:161], v82 offset:21248
	v_fmac_f32_e32 v147, v23, v158
	v_mul_f32_e32 v149, v194, v188
	v_fmac_f32_e32 v144, v146, v203
	v_fmac_f32_e32 v149, v62, v32
	v_fmac_f32_e32 v67, v22, v159
	v_mul_f32_e32 v69, v195, v154
	v_fmac_f32_e32 v143, v66, v204
	v_fmac_f32_e32 v148, v23, v159
	v_mul_f32_e32 v150, v195, v188
	v_fmac_f32_e32 v144, v147, v204
	s_nop 0
	v_fmac_f32_e32 v69, v145, v33
	v_fmac_f32_e32 v68, v22, v48
	v_fmac_f32_e32 v143, v67, v205
	v_fmac_f32_e32 v149, v23, v48
	v_fmac_f32_e32 v150, v151, v33
	v_mul_f32_e32 v151, v196, v188
	v_fmac_f32_e32 v144, v148, v205
	v_fmac_f32_e32 v69, v22, v49
	v_fmac_f32_e32 v143, v68, v224
	v_fmac_f32_e32 v150, v23, v49
	v_fmac_f32_e32 v151, v152, v34
	v_mul_f32_e32 v152, v197, v188
	v_fmac_f32_e32 v144, v149, v224
	v_fmac_f32_e32 v152, v153, v35
	v_fmac_f32_e32 v70, v22, v50
	v_fmac_f32_e32 v143, v69, v225
	v_fmac_f32_e32 v151, v23, v50
	v_fmac_f32_e32 v144, v150, v225
	v_lshl_add_u64 v[62:63], v[18:19], 0, s[8:9]
	v_fmac_f32_e32 v80, v22, v51
	v_fmac_f32_e32 v143, v70, v226
	v_fmac_f32_e32 v152, v23, v51
	v_fmac_f32_e32 v144, v151, v226
	global_load_dwordx4 v[18:21], v[62:63], off
	v_fmac_f32_e32 v143, v80, v227
	v_fmac_f32_e32 v144, v152, v227
	s_nop 0
	ds_read_b128 v[188:191], v83 offset:21504
	ds_read_b128 v[46:49], v83 offset:21520
	s_waitcnt lgkmcnt(12)
	v_mul_f32_e32 v145, v64, v58
	v_mul_f32_e32 v58, v81, v58
	v_fmac_f32_e32 v145, v65, v59
	v_fmac_f32_e32 v58, v146, v59
	v_fmac_f32_e32 v145, v66, v60
	v_fmac_f32_e32 v58, v147, v60
	v_fmac_f32_e32 v145, v67, v61
	v_fmac_f32_e32 v58, v148, v61
	s_waitcnt lgkmcnt(11)
	v_fmac_f32_e32 v145, v68, v54
	v_fmac_f32_e32 v58, v149, v54
	v_fmac_f32_e32 v145, v69, v55
	v_fmac_f32_e32 v58, v150, v55
	v_fmac_f32_e32 v145, v70, v56
	v_fmac_f32_e32 v58, v151, v56
	v_fmac_f32_e32 v145, v80, v57
	v_fmac_f32_e32 v58, v152, v57
	s_nop 1
	v_add_f32_dpp v145, v145, v145 quad_perm:[1,0,3,2] row_mask:0xf bank_mask:0xf bound_ctrl:1
	v_add_f32_dpp v58, v58, v58 quad_perm:[1,0,3,2] row_mask:0xf bank_mask:0xf bound_ctrl:1
	s_nop 0
	v_add_f32_dpp v145, v145, v145 quad_perm:[2,3,0,1] row_mask:0xf bank_mask:0xf bound_ctrl:1
	v_add_f32_dpp v58, v58, v58 quad_perm:[2,3,0,1] row_mask:0xf bank_mask:0xf bound_ctrl:1
	s_nop 0
	v_add_f32_dpp v145, v145, v145 row_half_mirror row_mask:0xf bank_mask:0xf bound_ctrl:1
	v_add_f32_dpp v58, v58, v58 row_half_mirror row_mask:0xf bank_mask:0xf bound_ctrl:1
	s_nop 0
	ds_read_b128 v[34:37], v83 offset:21760
	ds_read_b128 v[26:29], v83 offset:21776
	ds_read_b128 v[50:53], v83 offset:22016
	ds_read_b128 v[30:33], v83 offset:22032
	s_waitcnt lgkmcnt(11)
	v_mul_f32_e32 v157, v220, v145
	v_fmac_f32_e32 v157, v68, v206
	v_mul_f32_e32 v68, v221, v145
	v_mul_f32_e32 v153, v212, v145
	v_mul_f32_e32 v154, v213, v145
	v_mul_f32_e32 v155, v214, v145
	v_mul_f32_e32 v156, v215, v145
	v_fmac_f32_e32 v68, v69, v207
	v_mul_f32_e32 v69, v222, v145
	v_mul_f32_e32 v158, v223, v145
	v_fmac_f32_e32 v153, v64, v178
	v_fmac_f32_e32 v154, v65, v179
	v_fmac_f32_e32 v155, v66, v180
	v_fmac_f32_e32 v156, v67, v181
	v_fmac_f32_e32 v69, v70, v208
	v_fmac_f32_e32 v158, v80, v209
	s_nop 0
	s_waitcnt lgkmcnt(6)
	v_fmac_f32_e32 v153, v160, v228
	ds_read_b128 v[54:57], v83 offset:22272
	v_fmac_f32_e32 v154, v160, v229
	ds_read_b128 v[194:197], v83 offset:22288
	v_fmac_f32_e32 v155, v160, v230
	v_fmac_f32_e32 v156, v160, v231
	v_fmac_f32_e32 v157, v160, v238
	v_fmac_f32_e32 v68, v160, v239
	v_fmac_f32_e32 v69, v160, v240
	v_fmac_f32_e32 v158, v160, v241
	v_mul_f32_e32 v160, v215, v58
	v_mul_f32_e32 v80, v212, v58
	v_fmac_f32_e32 v160, v148, v181
	v_mul_f32_e32 v148, v220, v58
	ds_read_b128 v[202:205], v83 offset:22528
	ds_read_b128 v[224:227], v83 offset:22544
	v_mul_f32_e32 v162, v221, v58
	v_mul_f32_e32 v163, v222, v58
	v_mul_f32_e32 v164, v223, v58
	v_lshl_add_u64 v[66:67], v[62:63], 0, s[8:9]
	v_fmac_f32_e32 v80, v81, v178
	v_mul_f32_e32 v81, v213, v58
	v_mul_f32_e32 v159, v214, v58
	v_fmac_f32_e32 v148, v149, v206
	v_fmac_f32_e32 v162, v150, v207
	v_fmac_f32_e32 v163, v151, v208
	v_fmac_f32_e32 v164, v152, v209
	ds_read_b64 v[166:167], v82 offset:22784
	global_load_dwordx4 v[22:25], v[66:67], off
	v_fmac_f32_e32 v81, v146, v179
	v_fmac_f32_e32 v80, v161, v228
	v_fmac_f32_e32 v81, v161, v229
	v_fmac_f32_e32 v159, v147, v180
	s_waitcnt lgkmcnt(10)
	v_mul_f32_e32 v147, v153, v188
	v_mul_f32_e32 v188, v80, v188
	v_fmac_f32_e32 v159, v161, v230
	v_mul_f32_e32 v145, v42, v153
	v_mul_f32_e32 v146, v42, v80
	v_fmac_f32_e32 v160, v161, v231
	v_fmac_f32_e32 v147, v154, v189
	v_fmac_f32_e32 v188, v81, v189
	v_fmac_f32_e32 v145, v154, v43
	v_fmac_f32_e32 v146, v81, v43
	v_fmac_f32_e32 v148, v161, v238
	v_fmac_f32_e32 v147, v155, v190
	v_fmac_f32_e32 v188, v159, v190
	v_fmac_f32_e32 v145, v155, v44
	v_fmac_f32_e32 v146, v159, v44
	v_fmac_f32_e32 v162, v161, v239
	v_fmac_f32_e32 v147, v156, v191
	v_fmac_f32_e32 v188, v160, v191
	v_fmac_f32_e32 v145, v156, v45
	v_fmac_f32_e32 v163, v161, v240
	v_fmac_f32_e32 v164, v161, v241
	v_fmac_f32_e32 v146, v160, v45
	s_waitcnt lgkmcnt(9)
	v_fmac_f32_e32 v147, v157, v46
	v_fmac_f32_e32 v188, v148, v46
	s_nop 0
	v_fmac_f32_e32 v145, v157, v38
	v_fmac_f32_e32 v146, v148, v38
	v_fmac_f32_e32 v147, v68, v47
	v_fmac_f32_e32 v188, v162, v47
	v_fmac_f32_e32 v145, v68, v39
	v_fmac_f32_e32 v146, v162, v39
	s_nop 0
	v_fmac_f32_e32 v147, v69, v48
	v_fmac_f32_e32 v188, v163, v48
	v_fmac_f32_e32 v145, v69, v40
	v_fmac_f32_e32 v146, v163, v40
	v_fmac_f32_e32 v147, v158, v49
	v_fmac_f32_e32 v188, v164, v49
	v_fmac_f32_e32 v145, v158, v41
	v_fmac_f32_e32 v146, v164, v41
	s_nop 1
	s_nop 1
	v_add_f32_dpp v147, v147, v147 quad_perm:[1,0,3,2] row_mask:0xf bank_mask:0xf bound_ctrl:1
	v_add_f32_dpp v188, v188, v188 quad_perm:[1,0,3,2] row_mask:0xf bank_mask:0xf bound_ctrl:1
	s_nop 0
	v_add_f32_dpp v147, v147, v147 quad_perm:[2,3,0,1] row_mask:0xf bank_mask:0xf bound_ctrl:1
	v_add_f32_dpp v188, v188, v188 quad_perm:[2,3,0,1] row_mask:0xf bank_mask:0xf bound_ctrl:1
	s_nop 0
	v_add_f32_dpp v147, v147, v147 row_half_mirror row_mask:0xf bank_mask:0xf bound_ctrl:1
	v_add_f32_dpp v188, v188, v188 row_half_mirror row_mask:0xf bank_mask:0xf bound_ctrl:1
	s_waitcnt lgkmcnt(6)
	v_mul_f32_e32 v150, v52, v147
	v_fmac_f32_e32 v150, v155, v36
	ds_read_b128 v[46:49], v83 offset:23040
	ds_read_b128 v[42:45], v83 offset:23056
	v_mul_f32_e32 v151, v53, v147
	s_waitcnt lgkmcnt(7)
	v_mul_f32_e32 v155, v33, v147
	s_nop 0
	v_fmac_f32_e32 v151, v156, v37
	v_mul_f32_e32 v70, v50, v147
	v_mul_f32_e32 v152, v30, v147
	v_fmac_f32_e32 v155, v158, v29
	v_mul_f32_e32 v156, v50, v188
	v_mul_f32_e32 v158, v52, v188
	v_fmac_f32_e32 v70, v153, v34
	v_mul_f32_e32 v149, v51, v147
	v_fmac_f32_e32 v152, v157, v26
	v_fmac_f32_e32 v156, v80, v34
	v_mul_f32_e32 v157, v51, v188
	v_fmac_f32_e32 v158, v159, v36
	v_mul_f32_e32 v159, v53, v188
	ds_read_b128 v[50:53], v83 offset:23296
	v_fmac_f32_e32 v159, v160, v37
	s_waitcnt lgkmcnt(3)
	v_fmac_f32_e32 v70, v166, v54
	v_fmac_f32_e32 v149, v154, v35
	v_fmac_f32_e32 v156, v167, v54
	v_fmac_f32_e32 v157, v81, v35
	v_mul_f32_e32 v160, v30, v188
	s_nop 0
	v_mul_f32_e32 v153, v31, v147
	v_fmac_f32_e32 v149, v166, v55
	v_mul_f32_e32 v154, v32, v147
	v_mul_f32_e32 v147, v202, v70
	v_fmac_f32_e32 v157, v167, v55
	v_fmac_f32_e32 v160, v148, v26
	v_mul_f32_e32 v148, v202, v156
	s_nop 0
	v_fmac_f32_e32 v150, v166, v56
	v_fmac_f32_e32 v147, v149, v203
	v_fmac_f32_e32 v158, v167, v56
	v_fmac_f32_e32 v148, v157, v203
	v_fmac_f32_e32 v151, v166, v57
	v_fmac_f32_e32 v147, v150, v204
	v_fmac_f32_e32 v159, v167, v57
	v_mul_f32_e32 v161, v31, v188
	v_fmac_f32_e32 v148, v158, v204
	s_nop 0
	v_fmac_f32_e32 v153, v68, v27
	v_fmac_f32_e32 v152, v166, v194
	v_fmac_f32_e32 v147, v151, v205
	v_fmac_f32_e32 v160, v167, v194
	v_fmac_f32_e32 v161, v162, v27
	v_mul_f32_e32 v162, v32, v188
	v_fmac_f32_e32 v148, v159, v205
	v_fmac_f32_e32 v154, v69, v28
	v_fmac_f32_e32 v153, v166, v195
	v_fmac_f32_e32 v147, v152, v224
	v_fmac_f32_e32 v161, v167, v195
	v_fmac_f32_e32 v162, v163, v28
	v_mul_f32_e32 v163, v33, v188
	ds_read_b128 v[30:33], v83 offset:23312
	ds_read_b128 v[38:41], v83 offset:23552
	ds_read_b128 v[34:37], v83 offset:23568
	ds_read_b128 v[178:181], v83 offset:23808
	ds_read_b128 v[54:57], v83 offset:23824
	ds_read_b128 v[62:65], v83 offset:24064
	ds_read_b128 v[58:61], v83 offset:24080
	v_fmac_f32_e32 v148, v160, v224
	v_fmac_f32_e32 v163, v164, v29
	v_fmac_f32_e32 v154, v166, v196
	v_fmac_f32_e32 v147, v153, v225
	v_fmac_f32_e32 v162, v167, v196
	v_fmac_f32_e32 v148, v161, v225
	v_lshl_add_u64 v[80:81], v[66:67], 0, s[8:9]
	v_fmac_f32_e32 v155, v166, v197
	v_fmac_f32_e32 v147, v154, v226
	v_fmac_f32_e32 v163, v167, v197
	v_fmac_f32_e32 v148, v162, v226
	global_load_dwordx4 v[26:29], v[80:81], off
	v_fmac_f32_e32 v147, v155, v227
	v_fmac_f32_e32 v148, v163, v227
	s_nop 0
	s_waitcnt lgkmcnt(9)
	v_mul_f32_e32 v164, v70, v46
	v_mul_f32_e32 v165, v156, v46
	v_fmac_f32_e32 v164, v149, v47
	v_fmac_f32_e32 v165, v157, v47
	v_fmac_f32_e32 v164, v150, v48
	v_fmac_f32_e32 v165, v158, v48
	v_fmac_f32_e32 v164, v151, v49
	v_fmac_f32_e32 v165, v159, v49
	s_waitcnt lgkmcnt(8)
	v_fmac_f32_e32 v164, v152, v42
	v_fmac_f32_e32 v165, v160, v42
	v_fmac_f32_e32 v164, v153, v43
	v_fmac_f32_e32 v165, v161, v43
	v_fmac_f32_e32 v164, v154, v44
	v_fmac_f32_e32 v165, v162, v44
	v_fmac_f32_e32 v164, v155, v45
	v_fmac_f32_e32 v165, v163, v45
	s_nop 1
	v_add_f32_dpp v164, v164, v164 quad_perm:[1,0,3,2] row_mask:0xf bank_mask:0xf bound_ctrl:1
	v_add_f32_dpp v165, v165, v165 quad_perm:[1,0,3,2] row_mask:0xf bank_mask:0xf bound_ctrl:1
	s_nop 0
	v_add_f32_dpp v164, v164, v164 quad_perm:[2,3,0,1] row_mask:0xf bank_mask:0xf bound_ctrl:1
	v_add_f32_dpp v165, v165, v165 quad_perm:[2,3,0,1] row_mask:0xf bank_mask:0xf bound_ctrl:1
	s_nop 0
	v_add_f32_dpp v164, v164, v164 row_half_mirror row_mask:0xf bank_mask:0xf bound_ctrl:1
	v_add_f32_dpp v165, v165, v165 row_half_mirror row_mask:0xf bank_mask:0xf bound_ctrl:1
	s_waitcnt lgkmcnt(4)
	v_mul_f32_e32 v42, v34, v164
	v_mul_f32_e32 v43, v35, v164
	v_mul_f32_e32 v34, v34, v165
	v_mul_f32_e32 v35, v35, v165
	v_fmac_f32_e32 v42, v152, v30
	v_fmac_f32_e32 v43, v153, v31
	v_mul_f32_e32 v44, v36, v164
	v_mul_f32_e32 v45, v37, v164
	v_fmac_f32_e32 v34, v160, v30
	v_fmac_f32_e32 v35, v161, v31
	v_mul_f32_e32 v36, v36, v165
	v_mul_f32_e32 v37, v37, v165
	v_lshl_add_u64 v[30:31], v[80:81], 0, s[8:9]
	v_fmac_f32_e32 v44, v154, v32
	v_fmac_f32_e32 v45, v155, v33
	v_fmac_f32_e32 v36, v162, v32
	v_fmac_f32_e32 v37, v163, v33
	global_load_dwordx4 v[30:33], v[30:31], off
	ds_read_b64 v[82:83], v82 offset:24320
	v_mul_f32_e32 v46, v38, v164
	v_mul_f32_e32 v38, v38, v165
	v_fmac_f32_e32 v46, v70, v50
	v_mul_f32_e32 v47, v39, v164
	v_mul_f32_e32 v48, v40, v164
	v_mul_f32_e32 v49, v41, v164
	v_fmac_f32_e32 v38, v156, v50
	v_mul_f32_e32 v39, v39, v165
	v_fmac_f32_e32 v47, v149, v51
	s_waitcnt lgkmcnt(0)
	v_fmac_f32_e32 v46, v82, v178
	v_fmac_f32_e32 v48, v150, v52
	v_fmac_f32_e32 v49, v151, v53
	v_fmac_f32_e32 v38, v83, v178
	v_fmac_f32_e32 v39, v157, v51
	v_mul_f32_e32 v40, v40, v165
	s_nop 0
	v_fmac_f32_e32 v47, v82, v179
	v_fmac_f32_e32 v48, v82, v180
	v_fmac_f32_e32 v49, v82, v181
	v_fmac_f32_e32 v42, v82, v54
	v_fmac_f32_e32 v43, v82, v55
	v_fmac_f32_e32 v44, v82, v56
	v_fmac_f32_e32 v45, v82, v57
	v_mul_f32_e32 v82, v62, v46
	v_fmac_f32_e32 v39, v83, v179
	v_fmac_f32_e32 v40, v158, v52
	v_mul_f32_e32 v41, v41, v165
	v_mul_f32_e32 v50, v62, v38
	v_fmac_f32_e32 v40, v83, v180
	v_fmac_f32_e32 v82, v47, v63
	v_fmac_f32_e32 v41, v159, v53
	v_fmac_f32_e32 v50, v39, v63
	v_fmac_f32_e32 v41, v83, v181
	v_fmac_f32_e32 v82, v48, v64
	v_fmac_f32_e32 v50, v40, v64
	v_fmac_f32_e32 v34, v83, v54
	v_fmac_f32_e32 v82, v49, v65
	v_fmac_f32_e32 v50, v41, v65
	v_fmac_f32_e32 v35, v83, v55
	v_fmac_f32_e32 v82, v42, v58
	v_fmac_f32_e32 v50, v34, v58
	v_fmac_f32_e32 v36, v83, v56
	v_fmac_f32_e32 v82, v43, v59
	v_fmac_f32_e32 v50, v35, v59
	v_fmac_f32_e32 v37, v83, v57
	v_fmac_f32_e32 v82, v44, v60
	v_fmac_f32_e32 v50, v36, v60
	v_readlane_b32 s70, v237, 8
	v_fmac_f32_e32 v82, v45, v61
	v_fmac_f32_e32 v50, v37, v61
	v_readlane_b32 s71, v237, 9
	v_readlane_b32 s72, v237, 10
	v_readlane_b32 s73, v237, 11
	v_readlane_b32 s74, v237, 12
	v_readlane_b32 s75, v237, 13
	v_readlane_b32 s76, v237, 14
	v_readlane_b32 s77, v237, 15
	v_readlane_b32 s78, v237, 16
	v_readlane_b32 s79, v237, 17
	s_nop 1
	v_add_f32_dpp v135, v135, v135 quad_perm:[1,0,3,2] row_mask:0xf bank_mask:0xf bound_ctrl:1
	v_add_f32_dpp v136, v136, v136 quad_perm:[1,0,3,2] row_mask:0xf bank_mask:0xf bound_ctrl:1
	s_nop 0
	v_add_f32_dpp v135, v135, v135 quad_perm:[2,3,0,1] row_mask:0xf bank_mask:0xf bound_ctrl:1
	v_add_f32_dpp v136, v136, v136 quad_perm:[2,3,0,1] row_mask:0xf bank_mask:0xf bound_ctrl:1
	s_nop 0
	v_add_f32_dpp v135, v135, v135 row_half_mirror row_mask:0xf bank_mask:0xf bound_ctrl:1
	v_add_f32_dpp v136, v136, v136 row_half_mirror row_mask:0xf bank_mask:0xf bound_ctrl:1
	s_nop 1
	v_add_f32_dpp v137, v137, v137 quad_perm:[1,0,3,2] row_mask:0xf bank_mask:0xf bound_ctrl:1
	v_add_f32_dpp v138, v138, v138 quad_perm:[1,0,3,2] row_mask:0xf bank_mask:0xf bound_ctrl:1
	s_nop 0
	v_add_f32_dpp v137, v137, v137 quad_perm:[2,3,0,1] row_mask:0xf bank_mask:0xf bound_ctrl:1
	v_add_f32_dpp v138, v138, v138 quad_perm:[2,3,0,1] row_mask:0xf bank_mask:0xf bound_ctrl:1
	s_nop 0
	v_add_f32_dpp v137, v137, v137 row_half_mirror row_mask:0xf bank_mask:0xf bound_ctrl:1
	v_add_f32_dpp v138, v138, v138 row_half_mirror row_mask:0xf bank_mask:0xf bound_ctrl:1
	s_nop 1
	v_add_f32_dpp v139, v139, v139 quad_perm:[1,0,3,2] row_mask:0xf bank_mask:0xf bound_ctrl:1
	v_add_f32_dpp v140, v140, v140 quad_perm:[1,0,3,2] row_mask:0xf bank_mask:0xf bound_ctrl:1
	s_nop 0
	v_add_f32_dpp v139, v139, v139 quad_perm:[2,3,0,1] row_mask:0xf bank_mask:0xf bound_ctrl:1
	v_add_f32_dpp v140, v140, v140 quad_perm:[2,3,0,1] row_mask:0xf bank_mask:0xf bound_ctrl:1
	s_nop 0
	v_add_f32_dpp v139, v139, v139 row_half_mirror row_mask:0xf bank_mask:0xf bound_ctrl:1
	v_add_f32_dpp v140, v140, v140 row_half_mirror row_mask:0xf bank_mask:0xf bound_ctrl:1
	s_nop 1
	v_add_f32_dpp v141, v141, v141 quad_perm:[1,0,3,2] row_mask:0xf bank_mask:0xf bound_ctrl:1
	v_add_f32_dpp v142, v142, v142 quad_perm:[1,0,3,2] row_mask:0xf bank_mask:0xf bound_ctrl:1
	s_nop 0
	v_add_f32_dpp v141, v141, v141 quad_perm:[2,3,0,1] row_mask:0xf bank_mask:0xf bound_ctrl:1
	v_add_f32_dpp v142, v142, v142 quad_perm:[2,3,0,1] row_mask:0xf bank_mask:0xf bound_ctrl:1
	s_nop 0
	v_add_f32_dpp v141, v141, v141 row_half_mirror row_mask:0xf bank_mask:0xf bound_ctrl:1
	v_add_f32_dpp v142, v142, v142 row_half_mirror row_mask:0xf bank_mask:0xf bound_ctrl:1
	s_nop 1
	v_add_f32_dpp v143, v143, v143 quad_perm:[1,0,3,2] row_mask:0xf bank_mask:0xf bound_ctrl:1
	v_add_f32_dpp v144, v144, v144 quad_perm:[1,0,3,2] row_mask:0xf bank_mask:0xf bound_ctrl:1
	s_nop 0
	v_add_f32_dpp v143, v143, v143 quad_perm:[2,3,0,1] row_mask:0xf bank_mask:0xf bound_ctrl:1
	v_add_f32_dpp v144, v144, v144 quad_perm:[2,3,0,1] row_mask:0xf bank_mask:0xf bound_ctrl:1
	s_nop 0
	v_add_f32_dpp v143, v143, v143 row_half_mirror row_mask:0xf bank_mask:0xf bound_ctrl:1
	v_add_f32_dpp v144, v144, v144 row_half_mirror row_mask:0xf bank_mask:0xf bound_ctrl:1
	s_nop 1
	v_add_f32_dpp v145, v145, v145 quad_perm:[1,0,3,2] row_mask:0xf bank_mask:0xf bound_ctrl:1
	v_add_f32_dpp v146, v146, v146 quad_perm:[1,0,3,2] row_mask:0xf bank_mask:0xf bound_ctrl:1
	s_nop 0
	v_add_f32_dpp v145, v145, v145 quad_perm:[2,3,0,1] row_mask:0xf bank_mask:0xf bound_ctrl:1
	v_add_f32_dpp v146, v146, v146 quad_perm:[2,3,0,1] row_mask:0xf bank_mask:0xf bound_ctrl:1
	s_nop 0
	v_add_f32_dpp v145, v145, v145 row_half_mirror row_mask:0xf bank_mask:0xf bound_ctrl:1
	v_add_f32_dpp v146, v146, v146 row_half_mirror row_mask:0xf bank_mask:0xf bound_ctrl:1
	s_nop 1
	v_add_f32_dpp v147, v147, v147 quad_perm:[1,0,3,2] row_mask:0xf bank_mask:0xf bound_ctrl:1
	v_add_f32_dpp v148, v148, v148 quad_perm:[1,0,3,2] row_mask:0xf bank_mask:0xf bound_ctrl:1
	s_nop 0
	v_add_f32_dpp v147, v147, v147 quad_perm:[2,3,0,1] row_mask:0xf bank_mask:0xf bound_ctrl:1
	v_add_f32_dpp v148, v148, v148 quad_perm:[2,3,0,1] row_mask:0xf bank_mask:0xf bound_ctrl:1
	s_nop 0
	v_add_f32_dpp v147, v147, v147 row_half_mirror row_mask:0xf bank_mask:0xf bound_ctrl:1
	v_add_f32_dpp v148, v148, v148 row_half_mirror row_mask:0xf bank_mask:0xf bound_ctrl:1
	s_nop 1
	v_add_f32_dpp v82, v82, v82 quad_perm:[1,0,3,2] row_mask:0xf bank_mask:0xf bound_ctrl:1
	v_add_f32_dpp v50, v50, v50 quad_perm:[1,0,3,2] row_mask:0xf bank_mask:0xf bound_ctrl:1
	s_nop 0
	v_add_f32_dpp v82, v82, v82 quad_perm:[2,3,0,1] row_mask:0xf bank_mask:0xf bound_ctrl:1
	v_add_f32_dpp v50, v50, v50 quad_perm:[2,3,0,1] row_mask:0xf bank_mask:0xf bound_ctrl:1
	s_nop 0
	v_add_f32_dpp v82, v82, v82 row_half_mirror row_mask:0xf bank_mask:0xf bound_ctrl:1
	v_add_f32_dpp v50, v50, v50 row_half_mirror row_mask:0xf bank_mask:0xf bound_ctrl:1
	v_cvt_pk_f16_f32 v54, v95, v96
	v_cvt_pk_f16_f32 v55, v98, v99
	v_cvt_pk_f16_f32 v56, v103, v121
	v_cvt_pk_f16_f32 v57, v125, v126
	v_cvt_pk_f16_f32 v58, v127, v128
	v_cvt_pk_f16_f32 v59, v129, v130
	v_cvt_pk_f16_f32 v60, v131, v132
	v_cvt_pk_f16_f32 v61, v133, v134
	v_cvt_pk_f16_f32 v69, v135, v136
	v_cvt_pk_f16_f32 v68, v137, v138
	v_cvt_pk_f16_f32 v67, v139, v140
	v_cvt_pk_f16_f32 v66, v141, v142
	v_cvt_pk_f16_f32 v65, v143, v144
	v_cvt_pk_f16_f32 v64, v145, v146
	v_cvt_pk_f16_f32 v63, v147, v148
	v_cvt_pk_f16_f32 v62, v82, v50
	v_and_b32_e32 v50, 1, v168
	v_and_b32_e32 v51, 7, v168
	v_cmp_ne_u32_e32 vcc, 0, v50
	s_and_b64 s[10:11], s[80:81], exec
	s_cselect_b32 s12, s84, 0x400
	s_lshl_b32 s13, s46, 4
	v_lshlrev_b32_e32 v51, 1, v51
	v_and_b32_e32 v50, 2, v168
	v_cndmask_b32_e32 v54, v54, v56, vcc
	v_cndmask_b32_e32 v55, v55, v57, vcc
	v_cndmask_b32_e32 v58, v58, v60, vcc
	v_cndmask_b32_e32 v59, v59, v61, vcc
	v_cndmask_b32_e32 v69, v69, v67, vcc
	v_cndmask_b32_e32 v68, v68, v66, vcc
	v_cndmask_b32_e32 v65, v65, v63, vcc
	v_cndmask_b32_e32 v64, v64, v62, vcc
	v_cmp_ne_u32_e32 vcc, 0, v50
	s_sub_i32 s15, s12, s13
	s_add_i32 s15, s15, -16
	s_cmp_eq_u32 s90, 0
	s_cselect_b32 s15, s13, s15
	s_cselect_b32 s14, 0, 15
	v_and_b32_e32 v50, 4, v168
	v_xor_b32_e32 v52, s14, v51
	v_cndmask_b32_e32 v54, v54, v58, vcc
	v_cndmask_b32_e32 v55, v55, v59, vcc
	v_cndmask_b32_e32 v69, v69, v65, vcc
	v_cndmask_b32_e32 v68, v68, v64, vcc
	v_cmp_ne_u32_e32 vcc, 0, v50
	s_ashr_i32 s12, s92, 6
	s_lshl_b32 s13, s12, 10
	s_add_i32 s68, s13, 0x2000
	s_lshl_b32 s69, s12, 8
	s_and_b64 s[12:13], s[80:81], exec
	s_cselect_b32 s68, s69, s68
	s_add_i32 s15, s68, s15
	v_lshlrev_b32_e32 v52, 12, v52
	v_lshl_add_u32 v52, v72, 1, v52
	v_cndmask_b32_e32 v54, v54, v69, vcc
	v_cndmask_b32_e32 v55, v55, v68, vcc
	s_mul_i32 s16, s90, 0x3000000
	s_lshl_b32 s17, s93, 7
	s_add_i32 s16, s16, s17
	s_lshl_b32 s17, s4, 1
	s_add_i32 s16, s16, s17
	s_lshl_b32 s17, s15, 12
	s_add_i32 s16, s16, s17
	s_add_u32 s10, s5, s16
	s_addc_u32 s11, s42, 0
	v_xor_b32_e32 v53, 0x1000, v52
	s_mov_b64 s[8:9], exec
	global_store_dword v52, v54, s[10:11]
	global_store_dword v53, v55, s[10:11]
